# v016 + same staging remap (one wave fetches both 64-byte halves of its rows) applied to the P1, P4 and P7 GEMM instances as well
# baseline (speedup 1.0000x reference)
; #define PG8_STAGE(bufoff, gbase, voff) do { _Pragma("unroll") for (int _i = 0; _i < 2; ++_i) \
;         __builtin_amdgcn_global_load_lds((const unsigned*)((const char*)(gbase) + (voff)[_i]), (LAS unsigned*)(lds + (bufoff) + ldsw + _i * 8192), 16, 0, 0); } while (0)
; #define PG8_WAIT_V(n) asm volatile("s_waitcnt vmcnt(" #n ")" ::: "memory")
; #define PG8_BAR __builtin_amdgcn_s_barrier()
; template <class Epi, class Sched, bool ALIGN_EPI, bool SP2>
; __device__ __forceinline__ void gemm_phase(LAS unsigned char* lds, const Gemm g, const Sched& S, const Epi& E) {
;     ...
;     for (int i = 0; i < 2; ++i) { int R, C; stage_rc(tid * 16 + i * 8192, R, C); const int Rb = Epi::PERM ? ((R & ~31) + perm32(R & 31)) : R;
;         voffA[i] = (unsigned)(R * K + C) * 2u; voffB[i] = (unsigned)((Epi::BMODE ? 64 * Rb : Rb) * K + C) * 2u; }
;     const size_t kstep = (size_t)(BK * 2);
;     const size_t hstep = (size_t)HALF * K * 2;
;     const size_t tstep = 2 * hstep;
;     const size_t hstepB = Epi::BMODE ? (size_t)K * 2 : hstep;
;     ...
;     const unsigned ldsw = (unsigned)wid * 1024u;
;     const int aoff = lds_byte(wr * 64 + fr, fq * 8), boff = lds_byte(wc * 32 + fr, fq * 8);
;     ...
;     if constexpr (SP2) {
;         PG8_STAGE(PG8_SB(0, 0), cB, voffB); PG8_STAGE(PG8_SB(0, 1), cB + hstepB, voffB); PG8_STAGE(PG8_SA(0, 0), cA, voffA); PG8_STAGE(PG8_SA(0, 1), cA + hstep, voffA);
;         if (wr == 1) PG8_BAR;
;         PG8_WAIT_V(2); PG8_BAR;
;         PG8_STAGE(PG8_SB(1, 0), cB + kstep, voffB); PG8_STAGE(PG8_SA(1, 0), cA + kstep, voffA); PG8_STAGE(PG8_SB(1, 1), cB + hstepB + kstep, voffB);
;         PG8_WAIT_V(6); PG8_BAR;
.LBB0_383:
	s_add_u32 s50, s18, 0x16400000
	s_addc_u32 s51, s19, 0
	s_add_u32 s40, s18, 0x22400000
	s_addc_u32 s41, s19, 0
	s_ashr_i32 s21, s17, 31
	s_ashr_i32 s53, s16, 31
	s_add_u32 s0, s18, 0xc0000
	s_addc_u32 s1, s19, 0
	s_add_u32 s26, s18, 0x6400000
	s_addc_u32 s27, s19, 0
	s_andn2_b64 vcc, exec, s[2:3]
	s_cbranch_vccnz .LBB0_418
	v_ashrrev_i32_e32 v1, 31, v8
	v_lshrrev_b32_e32 v1, 26, v1
	v_add_u32_e32 v1, v8, v1
	v_ashrrev_i32_e32 v9, 6, v1
	v_lshlrev_b32_e32 v9, 1, v9
	v_bfe_i32 v1, v8, 27, 1
	v_lshlrev_b32_e32 v0, 4, v8
	v_lshrrev_b32_e32 v1, 22, v1
	v_add_u32_e32 v1, v0, v1
	v_and_b32_e32 v1, 0xfffffc00, v1
	v_sub_u32_e32 v1, v0, v1
	v_lshrrev_b32_e32 v2, 4, v1
	v_bitop3_b32 v1, v2, v1, 32 bitop3:0x6c
	v_ashrrev_i32_e32 v3, 31, v1
	v_lshrrev_b32_e32 v3, 26, v3
	v_add_u32_e32 v3, v1, v3
	v_lshlrev_b32_e32 v2, 3, v9
	v_ashrrev_i32_e32 v10, 6, v3
	v_and_b32_e32 v3, 0xc0, v3
	v_and_b32_e32 v2, -16, v2
	v_sub_u32_e32 v1, v1, v3
	v_mov_b32_e32 v3, 1
	v_add_u32_e32 v2, v10, v2
	v_ashrrev_i16_sdwa v1, v3, sext(v1) dst_sel:DWORD dst_unused:UNUSED_PAD src0_sel:DWORD src1_sel:BYTE_0
	v_lshlrev_b32_e32 v4, 5, v9
	v_bfe_i32 v11, v1, 0, 16
	v_lshlrev_b32_e32 v1, 1, v2
	v_lshrrev_b32_e32 v5, 2, v2
	v_and_b32_e32 v6, 3, v10
	s_mov_b32 s3, 0xfffe0
	v_and_b32_e32 v4, 32, v4
	v_and_b32_e32 v1, 24, v1
	v_and_b32_e32 v5, 4, v5
	v_and_or_b32 v6, v2, s3, v6
	v_or3_b32 v1, v6, v5, v1
	v_add_lshl_u32 v4, v4, v11, 1
	v_add_u32_e32 v0, 0x2000, v0
	v_lshl_add_u32 v144, v1, 12, v4
	v_ashrrev_i32_e32 v1, 31, v0
	v_lshrrev_b32_e32 v1, 22, v1
	v_add_u32_e32 v1, v0, v1
	v_ashrrev_i32_e32 v12, 10, v1
	v_mul_i32_i24_e32 v1, 0x400, v12
	v_lshl_add_u32 v12, v12, 1, -15
	v_sub_u32_e32 v0, v0, v1
	v_lshrrev_b32_e32 v1, 4, v0
	v_bitop3_b32 v0, v1, v0, 32 bitop3:0x6c
	v_lshl_add_u32 v142, v2, 12, v4
	v_ashrrev_i32_e32 v2, 31, v0
	v_lshrrev_b32_e32 v2, 26, v2
	v_add_u32_e32 v2, v0, v2
	v_lshlrev_b32_e32 v1, 3, v12
	v_ashrrev_i32_e32 v13, 6, v2
	v_and_b32_e32 v2, 0xc0, v2
	v_and_b32_e32 v1, -16, v1
	v_sub_u32_e32 v0, v0, v2
	s_ashr_i32 s2, s4, 6
	v_add_u32_e32 v1, v13, v1
	v_ashrrev_i16_sdwa v0, v3, sext(v0) dst_sel:DWORD dst_unused:UNUSED_PAD src0_sel:DWORD src1_sel:BYTE_0
	v_and_b32_e32 v3, 3, v13
	s_ashr_i32 s73, s72, 31
	s_ashr_i32 s71, s70, 31
	v_and_or_b32 v3, v1, s3, v3
	s_ashr_i32 s3, s4, 8
	s_lshl_b32 s57, s2, 11
	s_lshl_b64 s[14:15], s[72:73], 20
	s_lshl_b64 s[42:43], s[70:71], 20
	s_add_u32 s76, s6, s42
	v_lshlrev_b32_e32 v4, 5, v12
	v_bfe_i32 v14, v0, 0, 16
	v_lshlrev_b32_e32 v0, 1, v1
	v_lshrrev_b32_e32 v2, 2, v1
	s_addc_u32 s77, s7, s43
	s_add_i32 s59, s57, 0
	v_and_b32_e32 v4, 32, v4
	v_and_b32_e32 v0, 24, v0
	v_and_b32_e32 v2, 4, v2
	s_add_i32 m0, s59, 0x10000
	v_or3_b32 v0, v3, v2, v0
	v_add_lshl_u32 v2, v4, v14, 1
	global_load_lds_dwordx4 v144, s[76:77]
	s_add_i32 m0, s59, 0x10400
	v_lshl_add_u32 v148, v0, 12, v2
	s_add_u32 s42, s76, 0x80000
	global_load_lds_dwordx4 v148, s[76:77]
	s_addc_u32 s43, s77, 0
	s_add_i32 m0, s59, 0x14000
	v_lshl_add_u32 v146, v1, 12, v2
	global_load_lds_dwordx4 v144, s[42:43]
	s_add_i32 m0, s59, 0x14400
	s_add_u32 s74, s26, s14
	s_addc_u32 s75, s27, s15
	s_add_i32 s80, s59, 0x400
	global_load_lds_dwordx4 v148, s[42:43]
	s_mov_b32 m0, s59
	s_add_u32 s14, s74, 0x80000
	global_load_lds_dwordx4 v142, s[74:75]
	s_mov_b32 m0, s80
	s_addc_u32 s15, s75, 0
	s_add_i32 s81, s59, 0x4000
	global_load_lds_dwordx4 v146, s[74:75]
	s_mov_b32 m0, s81
	s_add_i32 s82, s59, 0x4400
	global_load_lds_dwordx4 v142, s[14:15]
	s_mov_b32 m0, s82
	v_mov_b32_e32 v151, 0
	global_load_lds_dwordx4 v146, s[14:15]
	v_mov_b32_e32 v145, v151
	v_mov_b32_e32 v149, v151
	v_mov_b32_e32 v143, v151
	v_mov_b32_e32 v147, v151
	s_cmp_eq_u32 s3, 1
	s_mov_b32 s83, 0
	v_lshl_add_u64 v[6:7], s[76:77], 0, v[144:145]
	v_lshl_add_u64 v[4:5], s[76:77], 0, v[148:149]
	v_lshl_add_u64 v[0:1], s[74:75], 0, v[142:143]
	s_cselect_b64 s[42:43], -1, 0
	s_cmp_lg_u32 s3, 1
	v_lshl_add_u64 v[2:3], s[74:75], 0, v[146:147]
	s_cbranch_scc1 .LBB0_386
	s_barrier
.LBB0_386:
	s_mov_b64 s[44:45], 0x80
	s_and_b32 s2, s2, 3
	s_add_i32 m0, s59, 0x18000
	v_lshl_add_u64 v[6:7], v[6:7], 0, s[44:45]
	s_lshl_b32 s5, s3, 13
	s_lshl_b32 s33, s2, 12
	s_waitcnt vmcnt(2)
	s_barrier
	global_load_lds_dwordx4 v[6:7], off
	v_lshl_add_u64 v[4:5], v[4:5], 0, s[44:45]
	s_add_i32 m0, s59, 0x18400
	s_add_i32 s84, s59, 0x8000
	s_add_i32 s85, s59, 0x8400
	global_load_lds_dwordx4 v[4:5], off
	v_lshl_add_u64 v[0:1], v[0:1], 0, s[44:45]
	s_mov_b32 m0, s84
	s_add_u32 s14, s76, 0x80080
	global_load_lds_dwordx4 v[0:1], off
	v_lshl_add_u64 v[0:1], v[2:3], 0, s[44:45]
	s_mov_b32 m0, s85
	s_addc_u32 s15, s77, 0
	global_load_lds_dwordx4 v[0:1], off
	s_add_i32 m0, s59, 0x1c000
	v_lshl_add_u64 v[0:1], s[14:15], 0, v[144:145]
	global_load_lds_dwordx4 v[0:1], off
	v_lshl_add_u64 v[0:1], s[14:15], 0, v[148:149]
	s_add_i32 m0, s59, 0x1c400
	v_lshlrev_b32_e32 v3, 2, v8
	global_load_lds_dwordx4 v[0:1], off
	v_bfe_u32 v1, v8, 4, 2
	v_and_b32_e32 v0, 15, v8
	v_lshlrev_b32_e32 v150, 4, v1
	v_lshl_or_b32 v168, s3, 6, v0
	v_lshl_or_b32 v0, v0, 6, v150
	v_and_b32_e32 v3, 32, v3
	v_bitop3_b32 v4, v0, s5, v3 bitop3:0xde
	v_bitop3_b32 v169, v0, s33, v3 bitop3:0xde
	v_lshlrev_b32_e32 v0, 15, v9
	v_lshlrev_b32_e32 v2, 3, v1
	v_and_b32_e32 v0, 0xffff0000, v0
	v_lshl_or_b32 v170, s2, 5, v2
	v_cmp_gt_u32_e64 s[2:3], 2, v1
	v_lshl_add_u32 v0, v10, 12, v0
	v_and_b32_e32 v1, 1, v9
	v_lshl_or_b32 v0, v1, 6, v0
	v_lshl_add_u32 v154, v11, 1, v0
	v_lshlrev_b32_e32 v0, 15, v12
	s_cmpk_lt_u32 s4, 0x100
	v_and_b32_e32 v0, 0xffff0000, v0
	s_waitcnt vmcnt(6)
	s_cselect_b64 s[46:47], -1, 0
	s_bitcmp0_b32 s4, 6
	v_lshl_add_u32 v0, v13, 12, v0
	v_and_b32_e32 v1, 1, v12
	s_cselect_b64 s[62:63], -1, 0
	v_lshl_or_b32 v0, v1, 6, v0
	s_add_i32 s87, 0, 0x10000
	s_add_i32 s88, 0, 0x14000
	v_lshl_add_u64 v[152:153], s[10:11], 0, v[150:151]
	v_mov_b32_e32 v155, v151
	v_lshl_add_u32 v156, v14, 1, v0
	v_mov_b32_e32 v157, v151
	v_mov_b64_e32 v[158:159], 0xd80
	v_mov_b64_e32 v[160:161], 0xd7f
	s_movk_i32 s86, 0x1b1
	v_add_u32_e32 v171, s87, v169
	v_add_u32_e32 v172, s88, v169
	v_add_u32_e32 v173, 0, v4
	s_barrier
	s_branch .LBB0_389

; #define PG8_STAGE(bufoff, gbase, voff) do { _Pragma("unroll") for (int _i = 0; _i < 2; ++_i) \
;         __builtin_amdgcn_global_load_lds((const unsigned*)((const char*)(gbase) + (voff)[_i]), (LAS unsigned*)(lds + (bufoff) + ldsw + _i * 8192), 16, 0, 0); } while (0)
; #define PG8_LDA(dst, b, h) do { _Pragma("unroll") for (int m = 0; m < 4; ++m) _Pragma("unroll") for (int k = 0; k < 2; ++k) dst[m][k] = *(const LAS bf16x8*)(lds + PG8_SA(b, h) + aoff + m * 2048 + k * 1024); } while (0)
; #define PG8_LDB(dst, b, h) do { _Pragma("unroll") for (int n = 0; n < 2; ++n) _Pragma("unroll") for (int k = 0; k < 2; ++k) dst[n][k] = *(const LAS bf16x8*)(lds + PG8_SB(b, h) + boff + n * 2048 + k * 1024); } while (0)
; #define PG8_MMA(ai, bj, At, Bt) do { __builtin_amdgcn_s_setprio(1); _Pragma("unroll") for (int m = 0; m < 4; ++m) _Pragma("unroll") for (int n = 0; n < 2; ++n) _Pragma("unroll") for (int k = 0; k < 2; ++k) \
;         acc[ai][bj][m][n] = __builtin_amdgcn_mfma_f32_16x16x32_bf16(Bt[n][k], At[m][k], acc[ai][bj][m][n], 0, 0, 0); __builtin_amdgcn_s_setprio(0); } while (0)
; #define PG8_WAIT_V(n) asm volatile("s_waitcnt vmcnt(" #n ")" ::: "memory")
; #define PG8_WAIT_L(n) asm volatile("s_waitcnt lgkmcnt(" #n ")" ::: "memory")
; #define PG8_BAR __builtin_amdgcn_s_barrier()
; #define PG8_SCHED __builtin_amdgcn_sched_barrier(0)
; template <class Epi, class Sched, bool ALIGN_EPI, bool SP2>
; __device__ __forceinline__ void gemm_phase(LAS unsigned char* lds, const Gemm g, const Sched& S, const Epi& E) {
;     ...
;             PG8_LDB(B0, 0, 0); PG8_LDB(B1, 0, 1); PG8_SCHED; PG8_LDA(At, 0, 0); PG8_STAGE(PG8_SA(1, 1), a1 + hstep, voffA);
;             PG8_WAIT_V(8); PG8_WAIT_L(0); PG8_BAR; PG8_MMA(0, 0, At, B0); PG8_MMA(0, 1, At, B1); PG8_BAR; PG8_SCHED;
;             PG8_LDA(At, 0, 1); PG8_STAGE(PG8_SB(0, 0), b2, voffB); PG8_STAGE(PG8_SB(0, 1), b2 + hstepB, voffB); PG8_STAGE(PG8_SA(0, 0), a2, voffA);
;             PG8_WAIT_V(8); PG8_WAIT_L(0); PG8_BAR; PG8_MMA(1, 0, At, B0); PG8_MMA(1, 1, At, B1); PG8_BAR; PG8_SCHED;
.LBB0_392:
	ds_read_b128 v[128:131], v171
	ds_read_b128 v[132:135], v171 offset:1024
	ds_read_b128 v[136:139], v171 offset:2048
	ds_read_b128 v[162:165], v171 offset:3072
	ds_read_b128 v[174:177], v172
	ds_read_b128 v[178:181], v172 offset:1024
	ds_read_b128 v[182:185], v172 offset:2048
	ds_read_b128 v[186:189], v172 offset:3072
	s_add_u32 s14, s74, 0xfff80080
	s_addc_u32 s15, s75, -1
	s_cmp_eq_u32 s73, 28
	s_cselect_b32 s79, s33, s15
	s_cselect_b32 s78, s48, s14
	s_cselect_b32 s77, s11, s71
	s_cselect_b32 s76, s49, s65
	v_lshl_add_u64 v[140:141], s[74:75], 0, v[154:155]
	s_add_i32 m0, s59, 0xc000
	ds_read_b128 v[190:193], v173
	ds_read_b128 v[194:197], v173 offset:1024
	ds_read_b128 v[198:201], v173 offset:2048
	ds_read_b128 v[202:205], v173 offset:3072
	ds_read_b128 v[208:211], v173 offset:4096
	ds_read_b128 v[212:215], v173 offset:5120
	ds_read_b128 v[216:219], v173 offset:6144
	ds_read_b128 v[220:223], v173 offset:7168
	global_load_lds_dwordx4 v[140:141], off
	v_lshl_add_u64 v[140:141], s[74:75], 0, v[156:157]
	s_add_i32 m0, s59, 0xc400
	s_nop 0
	global_load_lds_dwordx4 v[140:141], off
	s_waitcnt vmcnt(8)
	s_waitcnt lgkmcnt(0)
	s_barrier
	s_setprio 1
	v_mfma_f32_16x16x32_bf16 v[124:127], v[128:131], v[190:193], v[124:127]
	v_mfma_f32_16x16x32_bf16 v[120:123], v[136:139], v[190:193], v[120:123]
	v_mfma_f32_16x16x32_bf16 v[108:111], v[128:131], v[198:201], v[108:111]
	v_mfma_f32_16x16x32_bf16 v[104:107], v[136:139], v[198:201], v[104:107]
	v_mfma_f32_16x16x32_bf16 v[92:95], v[128:131], v[208:211], v[92:95]
	v_mfma_f32_16x16x32_bf16 v[88:91], v[136:139], v[208:211], v[88:91]
	v_mfma_f32_16x16x32_bf16 v[76:79], v[128:131], v[216:219], v[76:79]
	v_mfma_f32_16x16x32_bf16 v[72:75], v[136:139], v[216:219], v[72:75]
	v_mfma_f32_16x16x32_bf16 v[124:127], v[132:135], v[194:197], v[124:127]
	v_mfma_f32_16x16x32_bf16 v[120:123], v[162:165], v[194:197], v[120:123]
	v_mfma_f32_16x16x32_bf16 v[108:111], v[132:135], v[202:205], v[108:111]
	v_mfma_f32_16x16x32_bf16 v[104:107], v[162:165], v[202:205], v[104:107]
	v_mfma_f32_16x16x32_bf16 v[92:95], v[132:135], v[212:215], v[92:95]
	v_mfma_f32_16x16x32_bf16 v[88:91], v[162:165], v[212:215], v[88:91]
	v_mfma_f32_16x16x32_bf16 v[76:79], v[132:135], v[220:223], v[76:79]
	v_mfma_f32_16x16x32_bf16 v[72:75], v[162:165], v[220:223], v[72:75]
	v_mfma_f32_16x16x32_bf16 v[116:119], v[174:177], v[190:193], v[116:119]
	v_mfma_f32_16x16x32_bf16 v[112:115], v[182:185], v[190:193], v[112:115]
	v_mfma_f32_16x16x32_bf16 v[100:103], v[174:177], v[198:201], v[100:103]
	v_mfma_f32_16x16x32_bf16 v[96:99], v[182:185], v[198:201], v[96:99]
	v_mfma_f32_16x16x32_bf16 v[84:87], v[174:177], v[208:211], v[84:87]
	v_mfma_f32_16x16x32_bf16 v[80:83], v[182:185], v[208:211], v[80:83]
	v_mfma_f32_16x16x32_bf16 v[68:71], v[174:177], v[216:219], v[68:71]
	v_mfma_f32_16x16x32_bf16 v[64:67], v[182:185], v[216:219], v[64:67]
	v_mfma_f32_16x16x32_bf16 v[116:119], v[178:181], v[194:197], v[116:119]
	v_mfma_f32_16x16x32_bf16 v[112:115], v[186:189], v[194:197], v[112:115]
	v_mfma_f32_16x16x32_bf16 v[100:103], v[178:181], v[202:205], v[100:103]
	v_mfma_f32_16x16x32_bf16 v[96:99], v[186:189], v[202:205], v[96:99]
	v_mfma_f32_16x16x32_bf16 v[84:87], v[178:181], v[212:215], v[84:87]
	v_mfma_f32_16x16x32_bf16 v[80:83], v[186:189], v[212:215], v[80:83]
	v_mfma_f32_16x16x32_bf16 v[68:71], v[178:181], v[220:223], v[68:71]
	v_mfma_f32_16x16x32_bf16 v[64:67], v[186:189], v[220:223], v[64:67]
	s_setprio 0
	s_barrier
	s_add_i32 s14, s87, s57
	v_lshl_add_u64 v[140:141], s[76:77], 0, v[144:145]
	s_mov_b32 m0, s14
	ds_read_b128 v[190:193], v173 offset:16384
	ds_read_b128 v[194:197], v173 offset:17408
	ds_read_b128 v[198:201], v173 offset:18432
	ds_read_b128 v[202:205], v173 offset:19456
	ds_read_b128 v[208:211], v173 offset:20480
	ds_read_b128 v[212:215], v173 offset:21504
	ds_read_b128 v[216:219], v173 offset:22528
	ds_read_b128 v[220:223], v173 offset:23552
	global_load_lds_dwordx4 v[140:141], off
	s_add_i32 m0, s14, 0x400
	s_add_u32 s14, s76, 0x80000
	v_lshl_add_u64 v[166:167], s[76:77], 0, v[148:149]
	s_addc_u32 s15, s77, 0
	s_add_i32 s58, s88, s57
	global_load_lds_dwordx4 v[166:167], off
	v_lshl_add_u64 v[224:225], s[14:15], 0, v[144:145]
	s_mov_b32 m0, s58
	v_lshl_add_u64 v[226:227], s[78:79], 0, v[146:147]
	global_load_lds_dwordx4 v[224:225], off
	v_lshl_add_u64 v[224:225], s[14:15], 0, v[148:149]
	s_add_i32 m0, s58, 0x400
	s_nop 0
	global_load_lds_dwordx4 v[224:225], off
	v_lshl_add_u64 v[224:225], s[78:79], 0, v[142:143]
	s_mov_b32 m0, s59
	s_nop 0
	global_load_lds_dwordx4 v[224:225], off
	s_mov_b32 m0, s80
	s_nop 0
	global_load_lds_dwordx4 v[226:227], off
	s_waitcnt vmcnt(8)
	s_waitcnt lgkmcnt(0)
	s_barrier
; #define PG8_STAGE(bufoff, gbase, voff) do { _Pragma("unroll") for (int _i = 0; _i < 2; ++_i) \
;         __builtin_amdgcn_global_load_lds((const unsigned*)((const char*)(gbase) + (voff)[_i]), (LAS unsigned*)(lds + (bufoff) + ldsw + _i * 8192), 16, 0, 0); } while (0)
; #define PG8_LDA(dst, b, h) do { _Pragma("unroll") for (int m = 0; m < 4; ++m) _Pragma("unroll") for (int k = 0; k < 2; ++k) dst[m][k] = *(const LAS bf16x8*)(lds + PG8_SA(b, h) + aoff + m * 2048 + k * 1024); } while (0)
; #define PG8_LDB(dst, b, h) do { _Pragma("unroll") for (int n = 0; n < 2; ++n) _Pragma("unroll") for (int k = 0; k < 2; ++k) dst[n][k] = *(const LAS bf16x8*)(lds + PG8_SB(b, h) + boff + n * 2048 + k * 1024); } while (0)
; #define PG8_MMA(ai, bj, At, Bt) do { __builtin_amdgcn_s_setprio(1); _Pragma("unroll") for (int m = 0; m < 4; ++m) _Pragma("unroll") for (int n = 0; n < 2; ++n) _Pragma("unroll") for (int k = 0; k < 2; ++k) \
;         acc[ai][bj][m][n] = __builtin_amdgcn_mfma_f32_16x16x32_bf16(Bt[n][k], At[m][k], acc[ai][bj][m][n], 0, 0, 0); __builtin_amdgcn_s_setprio(0); } while (0)
; #define PG8_WAIT_V(n) asm volatile("s_waitcnt vmcnt(" #n ")" ::: "memory")
; #define PG8_WAIT_L(n) asm volatile("s_waitcnt lgkmcnt(" #n ")" ::: "memory")
; #define PG8_BAR __builtin_amdgcn_s_barrier()
; #define PG8_SCHED __builtin_amdgcn_sched_barrier(0)
; template <class Epi, class Sched, bool ALIGN_EPI, bool SP2>
; __device__ __forceinline__ void gemm_phase(LAS unsigned char* lds, const Gemm g, const Sched& S, const Epi& E) {
;     ...
;             PG8_WAIT_V(8); PG8_WAIT_L(0); PG8_BAR; PG8_MMA(1, 0, At, B0); PG8_MMA(1, 1, At, B1); PG8_BAR; PG8_SCHED;
;             PG8_LDB(B0, 1, 0); PG8_LDB(B1, 1, 1); PG8_SCHED; PG8_LDA(At, 1, 0); PG8_STAGE(PG8_SA(0, 1), a2 + hstep, voffA);
;             PG8_WAIT_V(8); PG8_WAIT_L(0); PG8_BAR; PG8_MMA(0, 0, At, B0); PG8_MMA(0, 1, At, B1); PG8_BAR; PG8_SCHED;
;             PG8_LDA(At, 1, 1); PG8_STAGE(PG8_SB(1, 0), b3, voffB); PG8_STAGE(PG8_SB(1, 1), b3 + hstepB, voffB); PG8_STAGE(PG8_SA(1, 0), a3, voffA);
	s_setprio 1
	v_mfma_f32_16x16x32_bf16 v[60:63], v[128:131], v[190:193], v[60:63]
	v_mfma_f32_16x16x32_bf16 v[56:59], v[136:139], v[190:193], v[56:59]
	v_mfma_f32_16x16x32_bf16 v[44:47], v[128:131], v[198:201], v[44:47]
	v_mfma_f32_16x16x32_bf16 v[40:43], v[136:139], v[198:201], v[40:43]
	v_mfma_f32_16x16x32_bf16 v[28:31], v[128:131], v[208:211], v[28:31]
	v_mfma_f32_16x16x32_bf16 v[24:27], v[136:139], v[208:211], v[24:27]
	v_mfma_f32_16x16x32_bf16 v[12:15], v[128:131], v[216:219], v[12:15]
	v_mfma_f32_16x16x32_bf16 v[8:11], v[136:139], v[216:219], v[8:11]
	v_mfma_f32_16x16x32_bf16 v[60:63], v[132:135], v[194:197], v[60:63]
	v_mfma_f32_16x16x32_bf16 v[56:59], v[162:165], v[194:197], v[56:59]
	v_mfma_f32_16x16x32_bf16 v[44:47], v[132:135], v[202:205], v[44:47]
	v_mfma_f32_16x16x32_bf16 v[40:43], v[162:165], v[202:205], v[40:43]
	v_mfma_f32_16x16x32_bf16 v[28:31], v[132:135], v[212:215], v[28:31]
	v_mfma_f32_16x16x32_bf16 v[24:27], v[162:165], v[212:215], v[24:27]
	v_mfma_f32_16x16x32_bf16 v[12:15], v[132:135], v[220:223], v[12:15]
	v_mfma_f32_16x16x32_bf16 v[8:11], v[162:165], v[220:223], v[8:11]
	v_mfma_f32_16x16x32_bf16 v[52:55], v[174:177], v[190:193], v[52:55]
	v_mfma_f32_16x16x32_bf16 v[48:51], v[182:185], v[190:193], v[48:51]
	v_mfma_f32_16x16x32_bf16 v[36:39], v[174:177], v[198:201], v[36:39]
	v_mfma_f32_16x16x32_bf16 v[32:35], v[182:185], v[198:201], v[32:35]
	v_mfma_f32_16x16x32_bf16 v[20:23], v[174:177], v[208:211], v[20:23]
	v_mfma_f32_16x16x32_bf16 v[16:19], v[182:185], v[208:211], v[16:19]
	v_mfma_f32_16x16x32_bf16 v[4:7], v[174:177], v[216:219], v[4:7]
	v_mfma_f32_16x16x32_bf16 v[0:3], v[182:185], v[216:219], v[0:3]
	v_mfma_f32_16x16x32_bf16 v[52:55], v[178:181], v[194:197], v[52:55]
	v_mfma_f32_16x16x32_bf16 v[48:51], v[186:189], v[194:197], v[48:51]
	v_mfma_f32_16x16x32_bf16 v[36:39], v[178:181], v[202:205], v[36:39]
	v_mfma_f32_16x16x32_bf16 v[32:35], v[186:189], v[202:205], v[32:35]
	v_mfma_f32_16x16x32_bf16 v[20:23], v[178:181], v[212:215], v[20:23]
	v_mfma_f32_16x16x32_bf16 v[16:19], v[186:189], v[212:215], v[16:19]
	v_mfma_f32_16x16x32_bf16 v[4:7], v[178:181], v[220:223], v[4:7]
	v_mfma_f32_16x16x32_bf16 v[0:3], v[186:189], v[220:223], v[0:3]
	s_setprio 0
	s_barrier
	s_add_i32 s58, 0, 0x18000
	v_add_u32_e32 v150, s58, v169
	s_add_i32 s89, 0, 0x1c000
	ds_read_b128 v[128:131], v150
	ds_read_b128 v[132:135], v150 offset:1024
	ds_read_b128 v[136:139], v150 offset:2048
	ds_read_b128 v[162:165], v150 offset:3072
	v_add_u32_e32 v150, s89, v169
	ds_read_b128 v[174:177], v150
	ds_read_b128 v[178:181], v150 offset:1024
	ds_read_b128 v[182:185], v150 offset:2048
	ds_read_b128 v[186:189], v150 offset:3072
	s_add_u32 s14, s78, 0x80000
	s_addc_u32 s15, s79, 0
	s_mov_b32 m0, s81
	v_lshl_add_u64 v[228:229], s[14:15], 0, v[142:143]
	ds_read_b128 v[190:193], v173 offset:32768
	ds_read_b128 v[194:197], v173 offset:33792
	ds_read_b128 v[198:201], v173 offset:34816
	ds_read_b128 v[202:205], v173 offset:35840
	ds_read_b128 v[208:211], v173 offset:36864
	ds_read_b128 v[212:215], v173 offset:37888
	ds_read_b128 v[216:219], v173 offset:38912
	ds_read_b128 v[220:223], v173 offset:39936
	global_load_lds_dwordx4 v[228:229], off
	v_lshl_add_u64 v[228:229], s[14:15], 0, v[146:147]
	s_mov_b32 m0, s82
	s_nop 0
	global_load_lds_dwordx4 v[228:229], off
	s_waitcnt vmcnt(8)
	s_waitcnt lgkmcnt(0)
	s_barrier
	s_setprio 1
	v_mfma_f32_16x16x32_bf16 v[124:127], v[128:131], v[190:193], v[124:127]
	v_mfma_f32_16x16x32_bf16 v[120:123], v[136:139], v[190:193], v[120:123]
	v_mfma_f32_16x16x32_bf16 v[108:111], v[128:131], v[198:201], v[108:111]
	v_mfma_f32_16x16x32_bf16 v[104:107], v[136:139], v[198:201], v[104:107]
	v_mfma_f32_16x16x32_bf16 v[92:95], v[128:131], v[208:211], v[92:95]
	v_mfma_f32_16x16x32_bf16 v[88:91], v[136:139], v[208:211], v[88:91]
	v_mfma_f32_16x16x32_bf16 v[76:79], v[128:131], v[216:219], v[76:79]
	v_mfma_f32_16x16x32_bf16 v[72:75], v[136:139], v[216:219], v[72:75]
	v_mfma_f32_16x16x32_bf16 v[124:127], v[132:135], v[194:197], v[124:127]
	v_mfma_f32_16x16x32_bf16 v[120:123], v[162:165], v[194:197], v[120:123]
	v_mfma_f32_16x16x32_bf16 v[108:111], v[132:135], v[202:205], v[108:111]
	v_mfma_f32_16x16x32_bf16 v[104:107], v[162:165], v[202:205], v[104:107]
	v_mfma_f32_16x16x32_bf16 v[92:95], v[132:135], v[212:215], v[92:95]
	v_mfma_f32_16x16x32_bf16 v[88:91], v[162:165], v[212:215], v[88:91]
	v_mfma_f32_16x16x32_bf16 v[76:79], v[132:135], v[220:223], v[76:79]
	v_mfma_f32_16x16x32_bf16 v[72:75], v[162:165], v[220:223], v[72:75]
	v_mfma_f32_16x16x32_bf16 v[116:119], v[174:177], v[190:193], v[116:119]
	v_mfma_f32_16x16x32_bf16 v[112:115], v[182:185], v[190:193], v[112:115]
	v_mfma_f32_16x16x32_bf16 v[100:103], v[174:177], v[198:201], v[100:103]
	v_mfma_f32_16x16x32_bf16 v[96:99], v[182:185], v[198:201], v[96:99]
	v_mfma_f32_16x16x32_bf16 v[84:87], v[174:177], v[208:211], v[84:87]
	v_mfma_f32_16x16x32_bf16 v[80:83], v[182:185], v[208:211], v[80:83]
	v_mfma_f32_16x16x32_bf16 v[68:71], v[174:177], v[216:219], v[68:71]
	v_mfma_f32_16x16x32_bf16 v[64:67], v[182:185], v[216:219], v[64:67]
	v_mfma_f32_16x16x32_bf16 v[116:119], v[178:181], v[194:197], v[116:119]
	v_mfma_f32_16x16x32_bf16 v[112:115], v[186:189], v[194:197], v[112:115]
	v_mfma_f32_16x16x32_bf16 v[100:103], v[178:181], v[202:205], v[100:103]
	v_mfma_f32_16x16x32_bf16 v[96:99], v[186:189], v[202:205], v[96:99]
	v_mfma_f32_16x16x32_bf16 v[84:87], v[178:181], v[212:215], v[84:87]
	v_mfma_f32_16x16x32_bf16 v[80:83], v[186:189], v[212:215], v[80:83]
	v_mfma_f32_16x16x32_bf16 v[68:71], v[178:181], v[220:223], v[68:71]
	v_mfma_f32_16x16x32_bf16 v[64:67], v[186:189], v[220:223], v[64:67]
	s_setprio 0
	s_barrier
; #define PG8_STAGE(bufoff, gbase, voff) do { _Pragma("unroll") for (int _i = 0; _i < 2; ++_i) \
;         __builtin_amdgcn_global_load_lds((const unsigned*)((const char*)(gbase) + (voff)[_i]), (LAS unsigned*)(lds + (bufoff) + ldsw + _i * 8192), 16, 0, 0); } while (0)
; #define PG8_LDA(dst, b, h) do { _Pragma("unroll") for (int m = 0; m < 4; ++m) _Pragma("unroll") for (int k = 0; k < 2; ++k) dst[m][k] = *(const LAS bf16x8*)(lds + PG8_SA(b, h) + aoff + m * 2048 + k * 1024); } while (0)
; #define PG8_MMA(ai, bj, At, Bt) do { __builtin_amdgcn_s_setprio(1); _Pragma("unroll") for (int m = 0; m < 4; ++m) _Pragma("unroll") for (int n = 0; n < 2; ++n) _Pragma("unroll") for (int k = 0; k < 2; ++k) \
;         acc[ai][bj][m][n] = __builtin_amdgcn_mfma_f32_16x16x32_bf16(Bt[n][k], At[m][k], acc[ai][bj][m][n], 0, 0, 0); __builtin_amdgcn_s_setprio(0); } while (0)
; #define PG8_WAIT_V(n) asm volatile("s_waitcnt vmcnt(" #n ")" ::: "memory")
; #define PG8_WAIT_L(n) asm volatile("s_waitcnt lgkmcnt(" #n ")" ::: "memory")
; #define PG8_BAR __builtin_amdgcn_s_barrier()
; #define PG8_SCHED __builtin_amdgcn_sched_barrier(0)
; template <class Epi, class Sched, bool ALIGN_EPI, bool SP2>
; __device__ __forceinline__ void gemm_phase(LAS unsigned char* lds, const Gemm g, const Sched& S, const Epi& E) {
;     ...
;             PG8_LDA(At, 1, 1); PG8_STAGE(PG8_SB(1, 0), b3, voffB); PG8_STAGE(PG8_SB(1, 1), b3 + hstepB, voffB); PG8_STAGE(PG8_SA(1, 0), a3, voffA);
;             PG8_WAIT_V(8); PG8_WAIT_L(0); PG8_BAR; PG8_MMA(1, 0, At, B0); PG8_MMA(1, 1, At, B1); PG8_BAR; PG8_SCHED;
	s_add_i32 s14, s58, s57
	v_lshl_add_u64 v[140:141], v[140:141], 0, s[44:45]
	s_mov_b32 m0, s14
	ds_read_b128 v[190:193], v173 offset:49152
	ds_read_b128 v[194:197], v173 offset:50176
	ds_read_b128 v[198:201], v173 offset:51200
	ds_read_b128 v[202:205], v173 offset:52224
	ds_read_b128 v[208:211], v173 offset:53248
	ds_read_b128 v[212:215], v173 offset:54272
	ds_read_b128 v[216:219], v173 offset:55296
	ds_read_b128 v[220:223], v173 offset:56320
	global_load_lds_dwordx4 v[140:141], off
	s_add_i32 m0, s14, 0x400
	s_add_u32 s14, s76, 0x80080
	v_lshl_add_u64 v[140:141], v[166:167], 0, s[44:45]
	s_addc_u32 s15, s77, 0
	s_add_i32 s58, s89, s57
	global_load_lds_dwordx4 v[140:141], off
	v_lshl_add_u64 v[140:141], s[14:15], 0, v[144:145]
	s_mov_b32 m0, s58
	s_nop 0
	global_load_lds_dwordx4 v[140:141], off
	v_lshl_add_u64 v[140:141], s[14:15], 0, v[148:149]
	s_add_i32 m0, s58, 0x400
	s_nop 0
	global_load_lds_dwordx4 v[140:141], off
	v_lshl_add_u64 v[140:141], v[224:225], 0, s[44:45]
	s_mov_b32 m0, s84
	s_nop 0
	global_load_lds_dwordx4 v[140:141], off
	v_lshl_add_u64 v[140:141], v[226:227], 0, s[44:45]
	s_mov_b32 m0, s85
	s_nop 0
	global_load_lds_dwordx4 v[140:141], off
	s_waitcnt vmcnt(8)
	s_waitcnt lgkmcnt(0)
	s_barrier
	s_setprio 1
	v_mfma_f32_16x16x32_bf16 v[60:63], v[128:131], v[190:193], v[60:63]
	v_mfma_f32_16x16x32_bf16 v[56:59], v[136:139], v[190:193], v[56:59]
	v_mfma_f32_16x16x32_bf16 v[44:47], v[128:131], v[198:201], v[44:47]
	v_mfma_f32_16x16x32_bf16 v[40:43], v[136:139], v[198:201], v[40:43]
	v_mfma_f32_16x16x32_bf16 v[28:31], v[128:131], v[208:211], v[28:31]
	v_mfma_f32_16x16x32_bf16 v[24:27], v[136:139], v[208:211], v[24:27]
	v_mfma_f32_16x16x32_bf16 v[12:15], v[128:131], v[216:219], v[12:15]
	v_mfma_f32_16x16x32_bf16 v[8:11], v[136:139], v[216:219], v[8:11]
	v_mfma_f32_16x16x32_bf16 v[60:63], v[132:135], v[194:197], v[60:63]
	v_mfma_f32_16x16x32_bf16 v[56:59], v[162:165], v[194:197], v[56:59]
	v_mfma_f32_16x16x32_bf16 v[44:47], v[132:135], v[202:205], v[44:47]
	v_mfma_f32_16x16x32_bf16 v[40:43], v[162:165], v[202:205], v[40:43]
	v_mfma_f32_16x16x32_bf16 v[28:31], v[132:135], v[212:215], v[28:31]
	v_mfma_f32_16x16x32_bf16 v[24:27], v[162:165], v[212:215], v[24:27]
	v_mfma_f32_16x16x32_bf16 v[12:15], v[132:135], v[220:223], v[12:15]
	v_mfma_f32_16x16x32_bf16 v[8:11], v[162:165], v[220:223], v[8:11]
	v_mfma_f32_16x16x32_bf16 v[52:55], v[174:177], v[190:193], v[52:55]
	v_mfma_f32_16x16x32_bf16 v[48:51], v[182:185], v[190:193], v[48:51]
	v_mfma_f32_16x16x32_bf16 v[36:39], v[174:177], v[198:201], v[36:39]
	v_mfma_f32_16x16x32_bf16 v[32:35], v[182:185], v[198:201], v[32:35]
	v_mfma_f32_16x16x32_bf16 v[20:23], v[174:177], v[208:211], v[20:23]
	v_mfma_f32_16x16x32_bf16 v[16:19], v[182:185], v[208:211], v[16:19]
	v_mfma_f32_16x16x32_bf16 v[4:7], v[174:177], v[216:219], v[4:7]
	v_mfma_f32_16x16x32_bf16 v[0:3], v[182:185], v[216:219], v[0:3]
	v_mfma_f32_16x16x32_bf16 v[52:55], v[178:181], v[194:197], v[52:55]
	v_mfma_f32_16x16x32_bf16 v[48:51], v[186:189], v[194:197], v[48:51]
	v_mfma_f32_16x16x32_bf16 v[36:39], v[178:181], v[202:205], v[36:39]
	v_mfma_f32_16x16x32_bf16 v[32:35], v[186:189], v[202:205], v[32:35]
	v_mfma_f32_16x16x32_bf16 v[20:23], v[178:181], v[212:215], v[20:23]
	v_mfma_f32_16x16x32_bf16 v[16:19], v[186:189], v[212:215], v[16:19]
	v_mfma_f32_16x16x32_bf16 v[4:7], v[178:181], v[220:223], v[4:7]
	v_mfma_f32_16x16x32_bf16 v[0:3], v[186:189], v[220:223], v[0:3]
	s_setprio 0
	s_barrier
	s_add_i32 s73, s73, 2
	s_add_u32 s74, s74, 0x100
	s_addc_u32 s75, s75, 0
	s_add_u32 s65, s65, 0x100
	s_addc_u32 s71, s71, 0
	s_cmp_gt_u32 s73, 29
	s_cbranch_scc0 .LBB0_392
	s_and_b64 vcc, exec, s[46:47]
	s_cbranch_vccz .LBB0_395
	s_barrier

; #define PG8_STAGE(bufoff, gbase, voff) do { _Pragma("unroll") for (int _i = 0; _i < 2; ++_i) \
;         __builtin_amdgcn_global_load_lds((const unsigned*)((const char*)(gbase) + (voff)[_i]), (LAS unsigned*)(lds + (bufoff) + ldsw + _i * 8192), 16, 0, 0); } while (0)
; #define PG8_WAIT_V(n) asm volatile("s_waitcnt vmcnt(" #n ")" ::: "memory")
; #define PG8_BAR __builtin_amdgcn_s_barrier()
; template <class Epi, class Sched, bool ALIGN_EPI, bool SP2>
; __device__ __forceinline__ void gemm_phase(LAS unsigned char* lds, const Gemm g, const Sched& S, const Epi& E) {
;     ...
;     for (int i = 0; i < 2; ++i) { int R, C; stage_rc(tid * 16 + i * 8192, R, C); const int Rb = Epi::PERM ? ((R & ~31) + perm32(R & 31)) : R;
;         voffA[i] = (unsigned)(R * K + C) * 2u; voffB[i] = (unsigned)((Epi::BMODE ? 64 * Rb : Rb) * K + C) * 2u; }
;     const size_t kstep = (size_t)(BK * 2);
;     const size_t hstep = (size_t)HALF * K * 2;
;     const size_t tstep = 2 * hstep;
;     const size_t hstepB = Epi::BMODE ? (size_t)K * 2 : hstep;
;     ...
;     const unsigned ldsw = (unsigned)wid * 1024u;
;     const int aoff = lds_byte(wr * 64 + fr, fq * 8), boff = lds_byte(wc * 32 + fr, fq * 8);
;     ...
;         PG8_STAGE(PG8_SB(0, 0), cB, voffB); PG8_STAGE(PG8_SB(0, 1), cB + hstepB, voffB); PG8_STAGE(PG8_SA(0, 0), cA, voffA); PG8_STAGE(PG8_SA(0, 1), cA + hstep, voffA);
;         if (wr == 1) PG8_BAR;
;         PG8_WAIT_V(2); PG8_BAR;
;         PG8_STAGE(PG8_SB(1, 0), cB + kstep, voffB); PG8_STAGE(PG8_SA(1, 0), cA + kstep, voffA); PG8_STAGE(PG8_SB(1, 1), cB + hstepB + kstep, voffB);
;         PG8_WAIT_V(6); PG8_BAR;
.LBB0_866:
	v_cndmask_b32_e64 v0, 0, 1, s[4:5]
	v_writelane_b32 v242, s94, 2
	s_add_u32 s0, s18, 0x60000
	v_cmp_ne_u32_e64 s[2:3], 1, v0
	v_writelane_b32 v242, s95, 3
	s_addc_u32 s1, s19, 0
	s_andn2_b64 vcc, exec, s[4:5]
	v_writelane_b32 v242, s2, 4
	s_nop 1
	v_writelane_b32 v242, s3, 5
	s_cbranch_vccnz .LBB0_907
	v_ashrrev_i32_e32 v2, 31, v1
	v_lshrrev_b32_e32 v2, 26, v2
	v_add_u32_e32 v2, v1, v2
	v_ashrrev_i32_e32 v10, 6, v2
	v_lshlrev_b32_e32 v10, 1, v10
	v_bfe_i32 v2, v1, 27, 1
	v_lshlrev_b32_e32 v0, 4, v1
	v_lshrrev_b32_e32 v2, 22, v2
	v_add_u32_e32 v2, v0, v2
	v_and_b32_e32 v2, 0xfffffc00, v2
	v_sub_u32_e32 v2, v0, v2
	v_lshrrev_b32_e32 v3, 4, v2
	v_bitop3_b32 v2, v3, v2, 32 bitop3:0x6c
	v_ashrrev_i32_e32 v4, 31, v2
	v_lshrrev_b32_e32 v4, 26, v4
	v_add_u32_e32 v4, v2, v4
	v_lshlrev_b32_e32 v3, 3, v10
	v_ashrrev_i32_e32 v11, 6, v4
	v_and_b32_e32 v4, 0xc0, v4
	v_and_b32_e32 v3, -16, v3
	v_sub_u32_e32 v2, v2, v4
	v_mov_b32_e32 v4, 1
	v_add_u32_e32 v3, v11, v3
	v_ashrrev_i16_sdwa v2, v4, sext(v2) dst_sel:DWORD dst_unused:UNUSED_PAD src0_sel:DWORD src1_sel:BYTE_0
	v_lshlrev_b32_e32 v5, 5, v10
	v_bfe_i32 v12, v2, 0, 16
	v_lshlrev_b32_e32 v2, 1, v3
	v_lshrrev_b32_e32 v6, 2, v3
	v_and_b32_e32 v7, 3, v11
	s_mov_b32 s5, 0xfffe0
	v_and_b32_e32 v5, 32, v5
	v_and_b32_e32 v2, 24, v2
	v_and_b32_e32 v6, 4, v6
	v_and_or_b32 v7, v3, s5, v7
	v_or3_b32 v2, v7, v6, v2
	v_add_lshl_u32 v5, v5, v12, 1
	v_add_u32_e32 v0, 0x2000, v0
	v_lshl_add_u32 v166, v2, 12, v5
	v_ashrrev_i32_e32 v2, 31, v0
	v_lshrrev_b32_e32 v2, 22, v2
	v_add_u32_e32 v2, v0, v2
	v_ashrrev_i32_e32 v13, 10, v2
	v_mul_i32_i24_e32 v2, 0x400, v13
	v_lshl_add_u32 v13, v13, 1, -15
	v_sub_u32_e32 v0, v0, v2
	v_lshrrev_b32_e32 v2, 4, v0
	v_bitop3_b32 v0, v2, v0, 32 bitop3:0x6c
	v_lshl_add_u32 v164, v3, 12, v5
	v_ashrrev_i32_e32 v3, 31, v0
	v_lshrrev_b32_e32 v3, 26, v3
	v_add_u32_e32 v3, v0, v3
	v_lshlrev_b32_e32 v2, 3, v13
	v_ashrrev_i32_e32 v14, 6, v3
	v_and_b32_e32 v3, 0xc0, v3
	v_and_b32_e32 v2, -16, v2
	v_sub_u32_e32 v0, v0, v3
	v_add_u32_e32 v2, v14, v2
	v_ashrrev_i16_sdwa v0, v4, sext(v0) dst_sel:DWORD dst_unused:UNUSED_PAD src0_sel:DWORD src1_sel:BYTE_0
	v_and_b32_e32 v4, 3, v14
	v_and_or_b32 v4, v2, s5, v4
	s_ashr_i32 s5, s6, 6
	s_ashr_i32 s11, s10, 31
	s_ashr_i32 s71, s70, 31
	s_ashr_i32 s4, s6, 8
	s_lshl_b32 s57, s5, 11
	s_lshl_b64 s[14:15], s[10:11], 20
	s_lshl_b64 s[40:41], s[70:71], 20
	s_add_u32 s74, s12, s40
	v_lshlrev_b32_e32 v5, 5, v13
	v_bfe_i32 v15, v0, 0, 16
	v_lshlrev_b32_e32 v0, 1, v2
	v_lshrrev_b32_e32 v3, 2, v2
	s_addc_u32 s75, s13, s41
	s_add_i32 s59, s57, 0
	v_and_b32_e32 v5, 32, v5
	v_and_b32_e32 v0, 24, v0
	v_and_b32_e32 v3, 4, v3
	s_add_i32 m0, s59, 0x10000
	v_or3_b32 v0, v4, v3, v0
	v_add_lshl_u32 v3, v5, v15, 1
	global_load_lds_dwordx4 v166, s[74:75]
	s_add_i32 m0, s59, 0x10400
	v_lshl_add_u32 v170, v0, 12, v3
	s_add_u32 s40, s74, 0x80000
	global_load_lds_dwordx4 v170, s[74:75]
	s_addc_u32 s41, s75, 0
	s_add_i32 m0, s59, 0x14000
	v_writelane_b32 v242, s91, 6
	global_load_lds_dwordx4 v166, s[40:41]
	s_add_i32 m0, s59, 0x14400
	s_add_u32 s76, s50, s14
	s_addc_u32 s77, s51, s15
	s_add_i32 s90, s59, 0x400
	global_load_lds_dwordx4 v170, s[40:41]
	s_mov_b32 m0, s59
	s_add_u32 s14, s76, 0x80000
	v_lshl_add_u32 v168, v2, 12, v3
	global_load_lds_dwordx4 v164, s[76:77]
	s_mov_b32 m0, s90
	s_addc_u32 s15, s77, 0
	s_add_i32 s91, s59, 0x4000
	s_mov_b64 s[2:3], s[34:35]
	s_mov_b64 s[34:35], s[92:93]
	global_load_lds_dwordx4 v168, s[76:77]
	s_mov_b32 m0, s91
	s_add_i32 s92, s59, 0x4400
	global_load_lds_dwordx4 v164, s[14:15]
	s_mov_b32 m0, s92
	v_mov_b32_e32 v0, 0
	global_load_lds_dwordx4 v168, s[14:15]
	v_mov_b32_e32 v167, v0
	v_mov_b32_e32 v171, v0
	v_mov_b32_e32 v165, v0
	v_mov_b32_e32 v169, v0
	s_cmp_eq_u32 s4, 1
	s_mov_b32 s11, 0
	v_lshl_add_u64 v[8:9], s[74:75], 0, v[166:167]
	v_lshl_add_u64 v[6:7], s[74:75], 0, v[170:171]
	v_lshl_add_u64 v[2:3], s[76:77], 0, v[164:165]
	s_cselect_b64 s[40:41], -1, 0
	s_cmp_lg_u32 s4, 1
	v_lshl_add_u64 v[4:5], s[76:77], 0, v[168:169]
	s_cbranch_scc1 .LBB0_869
	s_barrier
.LBB0_869:
	s_lshl_b32 s5, s5, 5
	s_mov_b64 s[42:43], 0x80
	s_and_b32 s33, s5, 0x60
	s_add_i32 m0, s59, 0x18000
	v_lshl_add_u64 v[8:9], v[8:9], 0, s[42:43]
	s_lshl_b32 s7, s4, 13
	s_lshl_b32 s5, s33, 7
	s_waitcnt vmcnt(2)
	s_barrier
	global_load_lds_dwordx4 v[8:9], off
	v_lshl_add_u64 v[6:7], v[6:7], 0, s[42:43]
	s_add_i32 m0, s59, 0x18400
	s_add_i32 s93, s59, 0x8000
	s_add_i32 s94, s59, 0x8400
	global_load_lds_dwordx4 v[6:7], off
	v_lshl_add_u64 v[2:3], v[2:3], 0, s[42:43]
	s_mov_b32 m0, s93
	s_add_u32 s14, s74, 0x80080
	global_load_lds_dwordx4 v[2:3], off
	v_lshl_add_u64 v[2:3], v[4:5], 0, s[42:43]
	s_mov_b32 m0, s94
	s_addc_u32 s15, s75, 0
	global_load_lds_dwordx4 v[2:3], off
	s_add_i32 m0, s59, 0x1c000
	v_lshl_add_u64 v[2:3], s[14:15], 0, v[166:167]
	global_load_lds_dwordx4 v[2:3], off
	v_lshl_add_u64 v[2:3], s[14:15], 0, v[170:171]
	s_add_i32 m0, s59, 0x1c400
	s_mov_b64 s[14:15], 0x80080
	global_load_lds_dwordx4 v[2:3], off
	v_bfe_u32 v3, v1, 4, 2
	v_and_b32_e32 v2, 15, v1
	v_lshlrev_b32_e32 v4, 4, v3
	v_lshlrev_b32_e32 v1, 2, v1
	v_lshl_or_b32 v184, s4, 6, v2
	v_lshl_or_b32 v2, v2, 6, v4
	v_and_b32_e32 v1, 32, v1
	v_bitop3_b32 v4, v2, s7, v1 bitop3:0xde
	v_bitop3_b32 v185, v2, s5, v1 bitop3:0xde
	v_lshlrev_b32_e32 v1, 15, v10
	v_and_b32_e32 v1, 0xffff0000, v1
	v_lshl_add_u32 v1, v11, 12, v1
	v_and_b32_e32 v2, 1, v10
	v_lshl_or_b32 v1, v2, 6, v1
	v_lshl_add_u32 v2, v12, 1, v1
	v_lshlrev_b32_e32 v1, 15, v13
	v_cmp_eq_u32_e64 s[4:5], 0, v3
	v_lshl_or_b32 v186, v3, 3, s33
	v_mov_b32_e32 v3, v0
	v_and_b32_e32 v1, 0xffff0000, v1
	v_lshl_add_u64 v[172:173], v[2:3], 0, s[14:15]
	v_lshl_add_u32 v1, v14, 12, v1
	v_and_b32_e32 v2, 1, v13
	s_waitcnt vmcnt(6)
	v_lshl_or_b32 v1, v2, 6, v1
	s_cmpk_lt_u32 s6, 0x100
	v_lshl_add_u32 v2, v15, 1, v1
	s_cselect_b64 s[44:45], -1, 0
	v_lshl_add_u64 v[174:175], v[2:3], 0, s[14:15]
	v_mov_b64_e32 v[176:177], 0x600
	v_mov_b64_e32 v[178:179], 0x5ff
	s_mov_b64 s[46:47], 0x100
	s_add_i32 s95, 0, 0x10000
	s_add_i32 s96, 0, 0x14000
	v_add_u32_e32 v187, 0, v4
	v_mov_b32_e32 v188, 0x358637bd
	v_mbcnt_hi_u32_b32 v189, -1, v207
	s_mov_b32 s97, 0
	s_barrier
	s_branch .LBB0_872

; #define PG8_STAGE(bufoff, gbase, voff) do { _Pragma("unroll") for (int _i = 0; _i < 2; ++_i) \
;         __builtin_amdgcn_global_load_lds((const unsigned*)((const char*)(gbase) + (voff)[_i]), (LAS unsigned*)(lds + (bufoff) + ldsw + _i * 8192), 16, 0, 0); } while (0)
; #define PG8_LDA(dst, b, h) do { _Pragma("unroll") for (int m = 0; m < 4; ++m) _Pragma("unroll") for (int k = 0; k < 2; ++k) dst[m][k] = *(const LAS bf16x8*)(lds + PG8_SA(b, h) + aoff + m * 2048 + k * 1024); } while (0)
; #define PG8_LDB(dst, b, h) do { _Pragma("unroll") for (int n = 0; n < 2; ++n) _Pragma("unroll") for (int k = 0; k < 2; ++k) dst[n][k] = *(const LAS bf16x8*)(lds + PG8_SB(b, h) + boff + n * 2048 + k * 1024); } while (0)
; #define PG8_MMA(ai, bj, At, Bt) do { __builtin_amdgcn_s_setprio(1); _Pragma("unroll") for (int m = 0; m < 4; ++m) _Pragma("unroll") for (int n = 0; n < 2; ++n) _Pragma("unroll") for (int k = 0; k < 2; ++k) \
;         acc[ai][bj][m][n] = __builtin_amdgcn_mfma_f32_16x16x32_bf16(Bt[n][k], At[m][k], acc[ai][bj][m][n], 0, 0, 0); __builtin_amdgcn_s_setprio(0); } while (0)
; #define PG8_WAIT_V(n) asm volatile("s_waitcnt vmcnt(" #n ")" ::: "memory")
; #define PG8_WAIT_L(n) asm volatile("s_waitcnt lgkmcnt(" #n ")" ::: "memory")
; #define PG8_BAR __builtin_amdgcn_s_barrier()
; #define PG8_SCHED __builtin_amdgcn_sched_barrier(0)
; template <class Epi, class Sched, bool ALIGN_EPI, bool SP2>
; __device__ __forceinline__ void gemm_phase(LAS unsigned char* lds, const Gemm g, const Sched& S, const Epi& E) {
;     ...
;             PG8_LDB(B0, 0, 0); PG8_LDB(B1, 0, 1); PG8_SCHED; PG8_LDA(At, 0, 0); PG8_STAGE(PG8_SA(1, 1), a1 + hstep, voffA);
;             PG8_WAIT_V(8); PG8_WAIT_L(0); PG8_BAR; PG8_MMA(0, 0, At, B0); PG8_MMA(0, 1, At, B1); PG8_BAR; PG8_SCHED;
;             PG8_LDA(At, 0, 1); PG8_STAGE(PG8_SB(0, 0), b2, voffB); PG8_STAGE(PG8_SB(0, 1), b2 + hstepB, voffB); PG8_STAGE(PG8_SA(0, 0), a2, voffA);
;             PG8_WAIT_V(8); PG8_WAIT_L(0); PG8_BAR; PG8_MMA(1, 0, At, B0); PG8_MMA(1, 1, At, B1); PG8_BAR; PG8_SCHED;
.LBB0_878:
	v_add_u32_e32 v1, s95, v185
	ds_read_b128 v[142:145], v1
	ds_read_b128 v[146:149], v1 offset:1024
	ds_read_b128 v[150:153], v1 offset:2048
	ds_read_b128 v[154:157], v1 offset:3072
	v_add_u32_e32 v1, s96, v185
	ds_read_b128 v[158:161], v1
	ds_read_b128 v[190:193], v1 offset:1024
	ds_read_b128 v[194:197], v1 offset:2048
	ds_read_b128 v[198:201], v1 offset:3072
	s_add_i32 s10, s10, 2
	s_add_u32 s14, s84, s76
	s_addc_u32 s15, s85, s77
	s_add_u32 s49, s82, s76
	s_addc_u32 s58, s83, s77
	s_cmp_eq_u32 s76, s80
	s_cselect_b32 s89, s65, s15
	s_cselect_b32 s88, s71, s14
	s_cselect_b32 s87, s63, s58
	s_cselect_b32 s86, s48, s49
	v_lshl_add_u64 v[162:163], v[140:141], 0, s[76:77]
	s_add_i32 m0, s59, 0xc000
	ds_read_b128 v[202:205], v187
	ds_read_b128 v[208:211], v187 offset:1024
	ds_read_b128 v[212:215], v187 offset:2048
	ds_read_b128 v[216:219], v187 offset:3072
	ds_read_b128 v[220:223], v187 offset:4096
	ds_read_b128 v[224:227], v187 offset:5120
	ds_read_b128 v[228:231], v187 offset:6144
	ds_read_b128 v[232:235], v187 offset:7168
	global_load_lds_dwordx4 v[162:163], off
	v_lshl_add_u64 v[162:163], v[2:3], 0, s[76:77]
	s_add_i32 m0, s59, 0xc400
	s_nop 0
	global_load_lds_dwordx4 v[162:163], off
	s_waitcnt vmcnt(8)
	s_waitcnt lgkmcnt(0)
	s_barrier
	s_setprio 1
	v_mfma_f32_16x16x32_bf16 v[128:131], v[142:145], v[202:205], v[128:131]
	v_mfma_f32_16x16x32_bf16 v[124:127], v[150:153], v[202:205], v[124:127]
	v_mfma_f32_16x16x32_bf16 v[112:115], v[142:145], v[212:215], v[112:115]
	v_mfma_f32_16x16x32_bf16 v[108:111], v[150:153], v[212:215], v[108:111]
	v_mfma_f32_16x16x32_bf16 v[96:99], v[142:145], v[220:223], v[96:99]
	v_mfma_f32_16x16x32_bf16 v[92:95], v[150:153], v[220:223], v[92:95]
	v_mfma_f32_16x16x32_bf16 v[80:83], v[142:145], v[228:231], v[80:83]
	v_mfma_f32_16x16x32_bf16 v[76:79], v[150:153], v[228:231], v[76:79]
	v_mfma_f32_16x16x32_bf16 v[128:131], v[146:149], v[208:211], v[128:131]
	v_mfma_f32_16x16x32_bf16 v[124:127], v[154:157], v[208:211], v[124:127]
	v_mfma_f32_16x16x32_bf16 v[112:115], v[146:149], v[216:219], v[112:115]
	v_mfma_f32_16x16x32_bf16 v[108:111], v[154:157], v[216:219], v[108:111]
	v_mfma_f32_16x16x32_bf16 v[96:99], v[146:149], v[224:227], v[96:99]
	v_mfma_f32_16x16x32_bf16 v[92:95], v[154:157], v[224:227], v[92:95]
	v_mfma_f32_16x16x32_bf16 v[80:83], v[146:149], v[232:235], v[80:83]
	v_mfma_f32_16x16x32_bf16 v[76:79], v[154:157], v[232:235], v[76:79]
	v_mfma_f32_16x16x32_bf16 v[120:123], v[158:161], v[202:205], v[120:123]
	v_mfma_f32_16x16x32_bf16 v[116:119], v[194:197], v[202:205], v[116:119]
	v_mfma_f32_16x16x32_bf16 v[104:107], v[158:161], v[212:215], v[104:107]
	v_mfma_f32_16x16x32_bf16 v[100:103], v[194:197], v[212:215], v[100:103]
	v_mfma_f32_16x16x32_bf16 v[88:91], v[158:161], v[220:223], v[88:91]
	v_mfma_f32_16x16x32_bf16 v[84:87], v[194:197], v[220:223], v[84:87]
	v_mfma_f32_16x16x32_bf16 v[72:75], v[158:161], v[228:231], v[72:75]
	v_mfma_f32_16x16x32_bf16 v[68:71], v[194:197], v[228:231], v[68:71]
	v_mfma_f32_16x16x32_bf16 v[120:123], v[190:193], v[208:211], v[120:123]
	v_mfma_f32_16x16x32_bf16 v[116:119], v[198:201], v[208:211], v[116:119]
	v_mfma_f32_16x16x32_bf16 v[104:107], v[190:193], v[216:219], v[104:107]
	v_mfma_f32_16x16x32_bf16 v[100:103], v[198:201], v[216:219], v[100:103]
	v_mfma_f32_16x16x32_bf16 v[88:91], v[190:193], v[224:227], v[88:91]
	v_mfma_f32_16x16x32_bf16 v[84:87], v[198:201], v[224:227], v[84:87]
	v_mfma_f32_16x16x32_bf16 v[72:75], v[190:193], v[232:235], v[72:75]
	v_mfma_f32_16x16x32_bf16 v[68:71], v[198:201], v[232:235], v[68:71]
	s_setprio 0
	s_barrier
	s_add_i32 s14, s95, s57
	v_lshl_add_u64 v[162:163], s[86:87], 0, v[166:167]
	s_mov_b32 m0, s14
	ds_read_b128 v[202:205], v187 offset:16384
	ds_read_b128 v[208:211], v187 offset:17408
	ds_read_b128 v[212:215], v187 offset:18432
	ds_read_b128 v[216:219], v187 offset:19456
	ds_read_b128 v[220:223], v187 offset:20480
	ds_read_b128 v[224:227], v187 offset:21504
	ds_read_b128 v[228:231], v187 offset:22528
	ds_read_b128 v[232:235], v187 offset:23552
	global_load_lds_dwordx4 v[162:163], off
	s_add_i32 m0, s14, 0x400
	s_add_u32 s14, s86, 0x80000
	v_lshl_add_u64 v[182:183], s[86:87], 0, v[170:171]
	s_addc_u32 s15, s87, 0
	s_add_i32 s49, s96, s57
	global_load_lds_dwordx4 v[182:183], off
	v_lshl_add_u64 v[236:237], s[14:15], 0, v[166:167]
	s_mov_b32 m0, s49
	v_lshl_add_u64 v[238:239], s[88:89], 0, v[168:169]
	global_load_lds_dwordx4 v[236:237], off
	v_lshl_add_u64 v[236:237], s[14:15], 0, v[170:171]
	s_add_i32 m0, s49, 0x400
	s_nop 0
	global_load_lds_dwordx4 v[236:237], off
	v_lshl_add_u64 v[236:237], s[88:89], 0, v[164:165]
	s_mov_b32 m0, s59
	s_nop 0
	global_load_lds_dwordx4 v[236:237], off
	s_mov_b32 m0, s90
	s_nop 0
	global_load_lds_dwordx4 v[238:239], off
	s_waitcnt vmcnt(8)
	s_waitcnt lgkmcnt(0)
	s_barrier
; #define PG8_STAGE(bufoff, gbase, voff) do { _Pragma("unroll") for (int _i = 0; _i < 2; ++_i) \
;         __builtin_amdgcn_global_load_lds((const unsigned*)((const char*)(gbase) + (voff)[_i]), (LAS unsigned*)(lds + (bufoff) + ldsw + _i * 8192), 16, 0, 0); } while (0)
; #define PG8_LDA(dst, b, h) do { _Pragma("unroll") for (int m = 0; m < 4; ++m) _Pragma("unroll") for (int k = 0; k < 2; ++k) dst[m][k] = *(const LAS bf16x8*)(lds + PG8_SA(b, h) + aoff + m * 2048 + k * 1024); } while (0)
; #define PG8_LDB(dst, b, h) do { _Pragma("unroll") for (int n = 0; n < 2; ++n) _Pragma("unroll") for (int k = 0; k < 2; ++k) dst[n][k] = *(const LAS bf16x8*)(lds + PG8_SB(b, h) + boff + n * 2048 + k * 1024); } while (0)
; #define PG8_MMA(ai, bj, At, Bt) do { __builtin_amdgcn_s_setprio(1); _Pragma("unroll") for (int m = 0; m < 4; ++m) _Pragma("unroll") for (int n = 0; n < 2; ++n) _Pragma("unroll") for (int k = 0; k < 2; ++k) \
;         acc[ai][bj][m][n] = __builtin_amdgcn_mfma_f32_16x16x32_bf16(Bt[n][k], At[m][k], acc[ai][bj][m][n], 0, 0, 0); __builtin_amdgcn_s_setprio(0); } while (0)
; #define PG8_WAIT_V(n) asm volatile("s_waitcnt vmcnt(" #n ")" ::: "memory")
; #define PG8_WAIT_L(n) asm volatile("s_waitcnt lgkmcnt(" #n ")" ::: "memory")
; #define PG8_BAR __builtin_amdgcn_s_barrier()
; #define PG8_SCHED __builtin_amdgcn_sched_barrier(0)
; template <class Epi, class Sched, bool ALIGN_EPI, bool SP2>
; __device__ __forceinline__ void gemm_phase(LAS unsigned char* lds, const Gemm g, const Sched& S, const Epi& E) {
;     ...
;             PG8_WAIT_V(8); PG8_WAIT_L(0); PG8_BAR; PG8_MMA(1, 0, At, B0); PG8_MMA(1, 1, At, B1); PG8_BAR; PG8_SCHED;
;             PG8_LDB(B0, 1, 0); PG8_LDB(B1, 1, 1); PG8_SCHED; PG8_LDA(At, 1, 0); PG8_STAGE(PG8_SA(0, 1), a2 + hstep, voffA);
;             PG8_WAIT_V(8); PG8_WAIT_L(0); PG8_BAR; PG8_MMA(0, 0, At, B0); PG8_MMA(0, 1, At, B1); PG8_BAR; PG8_SCHED;
;             PG8_LDA(At, 1, 1); PG8_STAGE(PG8_SB(1, 0), b3, voffB); PG8_STAGE(PG8_SB(1, 1), b3 + hstepB, voffB); PG8_STAGE(PG8_SA(1, 0), a3, voffA);
	s_setprio 1
	v_mfma_f32_16x16x32_bf16 v[64:67], v[142:145], v[202:205], v[64:67]
	v_mfma_f32_16x16x32_bf16 v[60:63], v[150:153], v[202:205], v[60:63]
	v_mfma_f32_16x16x32_bf16 v[48:51], v[142:145], v[212:215], v[48:51]
	v_mfma_f32_16x16x32_bf16 v[44:47], v[150:153], v[212:215], v[44:47]
	v_mfma_f32_16x16x32_bf16 v[32:35], v[142:145], v[220:223], v[32:35]
	v_mfma_f32_16x16x32_bf16 v[28:31], v[150:153], v[220:223], v[28:31]
	v_mfma_f32_16x16x32_bf16 v[16:19], v[142:145], v[228:231], v[16:19]
	v_mfma_f32_16x16x32_bf16 v[12:15], v[150:153], v[228:231], v[12:15]
	v_mfma_f32_16x16x32_bf16 v[64:67], v[146:149], v[208:211], v[64:67]
	v_mfma_f32_16x16x32_bf16 v[60:63], v[154:157], v[208:211], v[60:63]
	v_mfma_f32_16x16x32_bf16 v[48:51], v[146:149], v[216:219], v[48:51]
	v_mfma_f32_16x16x32_bf16 v[44:47], v[154:157], v[216:219], v[44:47]
	v_mfma_f32_16x16x32_bf16 v[32:35], v[146:149], v[224:227], v[32:35]
	v_mfma_f32_16x16x32_bf16 v[28:31], v[154:157], v[224:227], v[28:31]
	v_mfma_f32_16x16x32_bf16 v[16:19], v[146:149], v[232:235], v[16:19]
	v_mfma_f32_16x16x32_bf16 v[12:15], v[154:157], v[232:235], v[12:15]
	v_mfma_f32_16x16x32_bf16 v[56:59], v[158:161], v[202:205], v[56:59]
	v_mfma_f32_16x16x32_bf16 v[52:55], v[194:197], v[202:205], v[52:55]
	v_mfma_f32_16x16x32_bf16 v[40:43], v[158:161], v[212:215], v[40:43]
	v_mfma_f32_16x16x32_bf16 v[36:39], v[194:197], v[212:215], v[36:39]
	v_mfma_f32_16x16x32_bf16 v[24:27], v[158:161], v[220:223], v[24:27]
	v_mfma_f32_16x16x32_bf16 v[20:23], v[194:197], v[220:223], v[20:23]
	v_mfma_f32_16x16x32_bf16 v[8:11], v[158:161], v[228:231], v[8:11]
	v_mfma_f32_16x16x32_bf16 v[4:7], v[194:197], v[228:231], v[4:7]
	v_mfma_f32_16x16x32_bf16 v[56:59], v[190:193], v[208:211], v[56:59]
	v_mfma_f32_16x16x32_bf16 v[52:55], v[198:201], v[208:211], v[52:55]
	v_mfma_f32_16x16x32_bf16 v[40:43], v[190:193], v[216:219], v[40:43]
	v_mfma_f32_16x16x32_bf16 v[36:39], v[198:201], v[216:219], v[36:39]
	v_mfma_f32_16x16x32_bf16 v[24:27], v[190:193], v[224:227], v[24:27]
	v_mfma_f32_16x16x32_bf16 v[20:23], v[198:201], v[224:227], v[20:23]
	v_mfma_f32_16x16x32_bf16 v[8:11], v[190:193], v[232:235], v[8:11]
	v_mfma_f32_16x16x32_bf16 v[4:7], v[198:201], v[232:235], v[4:7]
	s_setprio 0
	s_barrier
	s_add_i32 s49, 0, 0x18000
	v_add_u32_e32 v1, s49, v185
	s_add_i32 s58, 0, 0x1c000
	ds_read_b128 v[142:145], v1
	ds_read_b128 v[146:149], v1 offset:1024
	ds_read_b128 v[150:153], v1 offset:2048
	ds_read_b128 v[154:157], v1 offset:3072
	v_add_u32_e32 v1, s58, v185
	ds_read_b128 v[158:161], v1
	ds_read_b128 v[190:193], v1 offset:1024
	ds_read_b128 v[194:197], v1 offset:2048
	ds_read_b128 v[198:201], v1 offset:3072
	s_add_u32 s14, s88, 0x80000
	s_addc_u32 s15, s89, 0
	s_mov_b32 m0, s91
	v_lshl_add_u64 v[240:241], s[14:15], 0, v[164:165]
	ds_read_b128 v[202:205], v187 offset:32768
	ds_read_b128 v[208:211], v187 offset:33792
	ds_read_b128 v[212:215], v187 offset:34816
	ds_read_b128 v[216:219], v187 offset:35840
	ds_read_b128 v[220:223], v187 offset:36864
	ds_read_b128 v[224:227], v187 offset:37888
	ds_read_b128 v[228:231], v187 offset:38912
	ds_read_b128 v[232:235], v187 offset:39936
	global_load_lds_dwordx4 v[240:241], off
	v_lshl_add_u64 v[240:241], s[14:15], 0, v[168:169]
	s_mov_b32 m0, s92
	s_nop 0
	global_load_lds_dwordx4 v[240:241], off
	s_waitcnt vmcnt(8)
	s_waitcnt lgkmcnt(0)
	s_barrier
	s_setprio 1
	v_mfma_f32_16x16x32_bf16 v[128:131], v[142:145], v[202:205], v[128:131]
	v_mfma_f32_16x16x32_bf16 v[124:127], v[150:153], v[202:205], v[124:127]
	v_mfma_f32_16x16x32_bf16 v[112:115], v[142:145], v[212:215], v[112:115]
	v_mfma_f32_16x16x32_bf16 v[108:111], v[150:153], v[212:215], v[108:111]
	v_mfma_f32_16x16x32_bf16 v[96:99], v[142:145], v[220:223], v[96:99]
	v_mfma_f32_16x16x32_bf16 v[92:95], v[150:153], v[220:223], v[92:95]
	v_mfma_f32_16x16x32_bf16 v[80:83], v[142:145], v[228:231], v[80:83]
	v_mfma_f32_16x16x32_bf16 v[76:79], v[150:153], v[228:231], v[76:79]
	v_mfma_f32_16x16x32_bf16 v[128:131], v[146:149], v[208:211], v[128:131]
	v_mfma_f32_16x16x32_bf16 v[124:127], v[154:157], v[208:211], v[124:127]
	v_mfma_f32_16x16x32_bf16 v[112:115], v[146:149], v[216:219], v[112:115]
	v_mfma_f32_16x16x32_bf16 v[108:111], v[154:157], v[216:219], v[108:111]
	v_mfma_f32_16x16x32_bf16 v[96:99], v[146:149], v[224:227], v[96:99]
	v_mfma_f32_16x16x32_bf16 v[92:95], v[154:157], v[224:227], v[92:95]
	v_mfma_f32_16x16x32_bf16 v[80:83], v[146:149], v[232:235], v[80:83]
	v_mfma_f32_16x16x32_bf16 v[76:79], v[154:157], v[232:235], v[76:79]
	v_mfma_f32_16x16x32_bf16 v[120:123], v[158:161], v[202:205], v[120:123]
	v_mfma_f32_16x16x32_bf16 v[116:119], v[194:197], v[202:205], v[116:119]
	v_mfma_f32_16x16x32_bf16 v[104:107], v[158:161], v[212:215], v[104:107]
	v_mfma_f32_16x16x32_bf16 v[100:103], v[194:197], v[212:215], v[100:103]
	v_mfma_f32_16x16x32_bf16 v[88:91], v[158:161], v[220:223], v[88:91]
	v_mfma_f32_16x16x32_bf16 v[84:87], v[194:197], v[220:223], v[84:87]
	v_mfma_f32_16x16x32_bf16 v[72:75], v[158:161], v[228:231], v[72:75]
	v_mfma_f32_16x16x32_bf16 v[68:71], v[194:197], v[228:231], v[68:71]
	v_mfma_f32_16x16x32_bf16 v[120:123], v[190:193], v[208:211], v[120:123]
	v_mfma_f32_16x16x32_bf16 v[116:119], v[198:201], v[208:211], v[116:119]
	v_mfma_f32_16x16x32_bf16 v[104:107], v[190:193], v[216:219], v[104:107]
	v_mfma_f32_16x16x32_bf16 v[100:103], v[198:201], v[216:219], v[100:103]
	v_mfma_f32_16x16x32_bf16 v[88:91], v[190:193], v[224:227], v[88:91]
	v_mfma_f32_16x16x32_bf16 v[84:87], v[198:201], v[224:227], v[84:87]
	v_mfma_f32_16x16x32_bf16 v[72:75], v[190:193], v[232:235], v[72:75]
	v_mfma_f32_16x16x32_bf16 v[68:71], v[198:201], v[232:235], v[68:71]
	s_setprio 0
	s_barrier
; #define PG8_STAGE(bufoff, gbase, voff) do { _Pragma("unroll") for (int _i = 0; _i < 2; ++_i) \
;         __builtin_amdgcn_global_load_lds((const unsigned*)((const char*)(gbase) + (voff)[_i]), (LAS unsigned*)(lds + (bufoff) + ldsw + _i * 8192), 16, 0, 0); } while (0)
; #define PG8_LDA(dst, b, h) do { _Pragma("unroll") for (int m = 0; m < 4; ++m) _Pragma("unroll") for (int k = 0; k < 2; ++k) dst[m][k] = *(const LAS bf16x8*)(lds + PG8_SA(b, h) + aoff + m * 2048 + k * 1024); } while (0)
; #define PG8_MMA(ai, bj, At, Bt) do { __builtin_amdgcn_s_setprio(1); _Pragma("unroll") for (int m = 0; m < 4; ++m) _Pragma("unroll") for (int n = 0; n < 2; ++n) _Pragma("unroll") for (int k = 0; k < 2; ++k) \
;         acc[ai][bj][m][n] = __builtin_amdgcn_mfma_f32_16x16x32_bf16(Bt[n][k], At[m][k], acc[ai][bj][m][n], 0, 0, 0); __builtin_amdgcn_s_setprio(0); } while (0)
; #define PG8_WAIT_V(n) asm volatile("s_waitcnt vmcnt(" #n ")" ::: "memory")
; #define PG8_WAIT_L(n) asm volatile("s_waitcnt lgkmcnt(" #n ")" ::: "memory")
; #define PG8_BAR __builtin_amdgcn_s_barrier()
; #define PG8_SCHED __builtin_amdgcn_sched_barrier(0)
; template <class Epi, class Sched, bool ALIGN_EPI, bool SP2>
; __device__ __forceinline__ void gemm_phase(LAS unsigned char* lds, const Gemm g, const Sched& S, const Epi& E) {
;     ...
;             PG8_LDA(At, 1, 1); PG8_STAGE(PG8_SB(1, 0), b3, voffB); PG8_STAGE(PG8_SB(1, 1), b3 + hstepB, voffB); PG8_STAGE(PG8_SA(1, 0), a3, voffA);
;             PG8_WAIT_V(8); PG8_WAIT_L(0); PG8_BAR; PG8_MMA(1, 0, At, B0); PG8_MMA(1, 1, At, B1); PG8_BAR; PG8_SCHED;
	s_add_i32 s14, s49, s57
	v_lshl_add_u64 v[162:163], v[162:163], 0, s[42:43]
	s_mov_b32 m0, s14
	ds_read_b128 v[202:205], v187 offset:49152
	ds_read_b128 v[208:211], v187 offset:50176
	ds_read_b128 v[212:215], v187 offset:51200
	ds_read_b128 v[216:219], v187 offset:52224
	ds_read_b128 v[220:223], v187 offset:53248
	ds_read_b128 v[224:227], v187 offset:54272
	ds_read_b128 v[228:231], v187 offset:55296
	ds_read_b128 v[232:235], v187 offset:56320
	global_load_lds_dwordx4 v[162:163], off
	s_add_i32 m0, s14, 0x400
	s_add_u32 s14, s86, 0x80080
	v_lshl_add_u64 v[162:163], v[182:183], 0, s[42:43]
	s_addc_u32 s15, s87, 0
	s_add_i32 s49, s58, s57
	global_load_lds_dwordx4 v[162:163], off
	v_lshl_add_u64 v[162:163], s[14:15], 0, v[166:167]
	s_mov_b32 m0, s49
	s_nop 0
	global_load_lds_dwordx4 v[162:163], off
	v_lshl_add_u64 v[162:163], s[14:15], 0, v[170:171]
	s_add_i32 m0, s49, 0x400
	s_nop 0
	global_load_lds_dwordx4 v[162:163], off
	v_lshl_add_u64 v[162:163], v[236:237], 0, s[42:43]
	s_mov_b32 m0, s93
	s_nop 0
	global_load_lds_dwordx4 v[162:163], off
	v_lshl_add_u64 v[162:163], v[238:239], 0, s[42:43]
	s_mov_b32 m0, s94
	s_nop 0
	global_load_lds_dwordx4 v[162:163], off
	s_waitcnt vmcnt(8)
	s_waitcnt lgkmcnt(0)
	s_barrier
	s_setprio 1
	v_mfma_f32_16x16x32_bf16 v[64:67], v[142:145], v[202:205], v[64:67]
	v_mfma_f32_16x16x32_bf16 v[60:63], v[150:153], v[202:205], v[60:63]
	v_mfma_f32_16x16x32_bf16 v[48:51], v[142:145], v[212:215], v[48:51]
	v_mfma_f32_16x16x32_bf16 v[44:47], v[150:153], v[212:215], v[44:47]
	v_mfma_f32_16x16x32_bf16 v[32:35], v[142:145], v[220:223], v[32:35]
	v_mfma_f32_16x16x32_bf16 v[28:31], v[150:153], v[220:223], v[28:31]
	v_mfma_f32_16x16x32_bf16 v[16:19], v[142:145], v[228:231], v[16:19]
	v_mfma_f32_16x16x32_bf16 v[12:15], v[150:153], v[228:231], v[12:15]
	v_mfma_f32_16x16x32_bf16 v[64:67], v[146:149], v[208:211], v[64:67]
	v_mfma_f32_16x16x32_bf16 v[60:63], v[154:157], v[208:211], v[60:63]
	v_mfma_f32_16x16x32_bf16 v[48:51], v[146:149], v[216:219], v[48:51]
	v_mfma_f32_16x16x32_bf16 v[44:47], v[154:157], v[216:219], v[44:47]
	v_mfma_f32_16x16x32_bf16 v[32:35], v[146:149], v[224:227], v[32:35]
	v_mfma_f32_16x16x32_bf16 v[28:31], v[154:157], v[224:227], v[28:31]
	v_mfma_f32_16x16x32_bf16 v[16:19], v[146:149], v[232:235], v[16:19]
	v_mfma_f32_16x16x32_bf16 v[12:15], v[154:157], v[232:235], v[12:15]
	v_mfma_f32_16x16x32_bf16 v[56:59], v[158:161], v[202:205], v[56:59]
	v_mfma_f32_16x16x32_bf16 v[52:55], v[194:197], v[202:205], v[52:55]
	v_mfma_f32_16x16x32_bf16 v[40:43], v[158:161], v[212:215], v[40:43]
	v_mfma_f32_16x16x32_bf16 v[36:39], v[194:197], v[212:215], v[36:39]
	v_mfma_f32_16x16x32_bf16 v[24:27], v[158:161], v[220:223], v[24:27]
	v_mfma_f32_16x16x32_bf16 v[20:23], v[194:197], v[220:223], v[20:23]
	v_mfma_f32_16x16x32_bf16 v[8:11], v[158:161], v[228:231], v[8:11]
	v_mfma_f32_16x16x32_bf16 v[4:7], v[194:197], v[228:231], v[4:7]
	v_mfma_f32_16x16x32_bf16 v[56:59], v[190:193], v[208:211], v[56:59]
	v_mfma_f32_16x16x32_bf16 v[52:55], v[198:201], v[208:211], v[52:55]
	v_mfma_f32_16x16x32_bf16 v[40:43], v[190:193], v[216:219], v[40:43]
	v_mfma_f32_16x16x32_bf16 v[36:39], v[198:201], v[216:219], v[36:39]
	v_mfma_f32_16x16x32_bf16 v[24:27], v[190:193], v[224:227], v[24:27]
	v_mfma_f32_16x16x32_bf16 v[20:23], v[198:201], v[224:227], v[20:23]
	v_mfma_f32_16x16x32_bf16 v[8:11], v[190:193], v[232:235], v[8:11]
	v_mfma_f32_16x16x32_bf16 v[4:7], v[198:201], v[232:235], v[4:7]
	s_setprio 0
	s_barrier
	s_add_u32 s84, s84, 0x100
	s_addc_u32 s85, s85, 0
	s_add_u32 s82, s82, 0x100
	s_addc_u32 s83, s83, 0
	s_add_u32 s80, s80, 0xffffff00
	s_addc_u32 s81, s81, -1
	v_lshl_add_u64 v[140:141], v[140:141], 0, s[46:47]
	s_cmp_ge_u32 s10, s33
	v_lshl_add_u64 v[2:3], v[2:3], 0, s[46:47]
	s_cbranch_scc0 .LBB0_878

; #define PG8_STAGE(bufoff, gbase, voff) do { _Pragma("unroll") for (int _i = 0; _i < 2; ++_i) \
;         __builtin_amdgcn_global_load_lds((const unsigned*)((const char*)(gbase) + (voff)[_i]), (LAS unsigned*)(lds + (bufoff) + ldsw + _i * 8192), 16, 0, 0); } while (0)
; #define PG8_WAIT_V(n) asm volatile("s_waitcnt vmcnt(" #n ")" ::: "memory")
; #define PG8_BAR __builtin_amdgcn_s_barrier()
; template <class Epi, class Sched, bool ALIGN_EPI, bool SP2>
; __device__ __forceinline__ void gemm_phase(LAS unsigned char* lds, const Gemm g, const Sched& S, const Epi& E) {
;     ...
;     for (int i = 0; i < 2; ++i) { int R, C; stage_rc(tid * 16 + i * 8192, R, C); const int Rb = Epi::PERM ? ((R & ~31) + perm32(R & 31)) : R;
;         voffA[i] = (unsigned)(R * K + C) * 2u; voffB[i] = (unsigned)((Epi::BMODE ? 64 * Rb : Rb) * K + C) * 2u; }
;     const size_t kstep = (size_t)(BK * 2);
;     const size_t hstep = (size_t)HALF * K * 2;
;     const size_t tstep = 2 * hstep;
;     const size_t hstepB = Epi::BMODE ? (size_t)K * 2 : hstep;
;     ...
;     const unsigned ldsw = (unsigned)wid * 1024u;
;     const int aoff = lds_byte(wr * 64 + fr, fq * 8), boff = lds_byte(wc * 32 + fr, fq * 8);
;     ...
;         PG8_STAGE(PG8_SB(0, 0), cB, voffB); PG8_STAGE(PG8_SB(0, 1), cB + hstepB, voffB); PG8_STAGE(PG8_SA(0, 0), cA, voffA); PG8_STAGE(PG8_SA(0, 1), cA + hstep, voffA);
;         if (wr == 1) PG8_BAR;
;         PG8_WAIT_V(2); PG8_BAR;
;         PG8_STAGE(PG8_SB(1, 0), cB + kstep, voffB); PG8_STAGE(PG8_SA(1, 0), cA + kstep, voffA); PG8_STAGE(PG8_SB(1, 1), cB + hstepB + kstep, voffB);
;         PG8_WAIT_V(6); PG8_BAR;
.LBB0_1127:
	s_add_u32 s6, s18, 0x90000
	s_addc_u32 s7, s19, 0
	s_and_b64 vcc, exec, s[2:3]
	s_cbranch_vccnz .LBB0_1163
	v_ashrrev_i32_e32 v1, 31, v8
	v_lshrrev_b32_e32 v1, 26, v1
	v_add_u32_e32 v1, v8, v1
	v_ashrrev_i32_e32 v9, 6, v1
	v_lshlrev_b32_e32 v9, 1, v9
	v_bfe_i32 v1, v8, 27, 1
	v_lshlrev_b32_e32 v0, 4, v8
	v_lshrrev_b32_e32 v1, 22, v1
	v_add_u32_e32 v1, v0, v1
	v_and_b32_e32 v1, 0xfffffc00, v1
	v_sub_u32_e32 v1, v0, v1
	v_lshrrev_b32_e32 v2, 4, v1
	v_bitop3_b32 v1, v2, v1, 32 bitop3:0x6c
	v_ashrrev_i32_e32 v3, 31, v1
	v_lshrrev_b32_e32 v3, 26, v3
	v_lshlrev_b32_e32 v2, 3, v9
	v_add_u32_e32 v3, v1, v3
	v_and_b32_e32 v2, -16, v2
	v_ashrrev_i32_e32 v10, 6, v3
	v_and_b32_e32 v3, 0xc0, v3
	v_add_u32_e32 v2, v10, v2
	v_lshlrev_b32_e32 v4, 5, v9
	v_sub_u32_e32 v1, v1, v3
	v_mov_b32_e32 v3, 1
	v_and_b32_e32 v11, 32, v4
	v_ashrrev_i16_sdwa v1, v3, sext(v1) dst_sel:DWORD dst_unused:UNUSED_PAD src0_sel:DWORD src1_sel:BYTE_0
	v_lshlrev_b32_e32 v4, 1, v2
	v_lshrrev_b32_e32 v5, 2, v2
	v_and_b32_e32 v6, 3, v10
	s_mov_b32 s2, 0x7fffe0
	v_bfe_i32 v12, v1, 0, 16
	v_and_b32_e32 v4, 24, v4
	v_and_b32_e32 v5, 4, v5
	v_and_or_b32 v6, v2, s2, v6
	s_movk_i32 s4, 0x1600
	v_add_u32_e32 v1, v11, v12
	v_or3_b32 v4, v6, v5, v4
	v_mul_lo_u32 v2, v2, s4
	v_add_lshl_u32 v136, v1, v2, 1
	v_mul_u32_u24_e32 v2, 0x1600, v4
	v_add_u32_e32 v0, 0x2000, v0
	v_add_lshl_u32 v138, v2, v1, 1
	v_ashrrev_i32_e32 v1, 31, v0
	v_lshrrev_b32_e32 v1, 22, v1
	v_add_u32_e32 v1, v0, v1
	v_ashrrev_i32_e32 v13, 10, v1
	v_mul_i32_i24_e32 v1, 0x400, v13
	v_lshl_add_u32 v13, v13, 1, -15
	v_sub_u32_e32 v0, v0, v1
	v_lshrrev_b32_e32 v1, 4, v0
	v_bitop3_b32 v0, v1, v0, 32 bitop3:0x6c
	v_ashrrev_i32_e32 v2, 31, v0
	v_lshrrev_b32_e32 v2, 26, v2
	v_lshlrev_b32_e32 v1, 3, v13
	v_add_u32_e32 v2, v0, v2
	v_and_b32_e32 v1, -16, v1
	v_ashrrev_i32_e32 v14, 6, v2
	v_lshlrev_b32_e32 v4, 5, v13
	v_add_u32_e32 v1, v14, v1
	v_and_b32_e32 v15, 32, v4
	v_and_b32_e32 v4, 3, v14
	v_and_b32_e32 v2, 0xc0, v2
	v_and_or_b32 v4, v1, s2, v4
	s_ashr_i32 s2, s0, 6
	s_ashr_i32 s1, s0, 8
	v_sub_u32_e32 v0, v0, v2
	s_lshl_b32 s44, s2, 11
	s_mul_i32 s9, s48, 0x2c0000
	v_ashrrev_i16_sdwa v0, v3, sext(v0) dst_sel:DWORD dst_unused:UNUSED_PAD src0_sel:DWORD src1_sel:BYTE_0
	v_lshlrev_b32_e32 v2, 1, v1
	v_lshrrev_b32_e32 v3, 2, v1
	s_mul_hi_i32 s8, s48, 0x2c0000
	s_add_u32 s38, s54, s9
	v_bfe_i32 v16, v0, 0, 16
	v_and_b32_e32 v2, 24, v2
	v_and_b32_e32 v3, 4, v3
	s_addc_u32 s39, s55, s8
	s_add_i32 s45, s44, 0
	v_add_u32_e32 v0, v15, v16
	v_or3_b32 v2, v4, v3, v2
	v_mul_lo_u32 v1, v1, s4
	s_add_i32 m0, s45, 0x10000
	v_add_lshl_u32 v140, v0, v1, 1
	v_mul_u32_u24_e32 v1, 0x1600, v2
	global_load_lds_dwordx4 v138, s[38:39]
	s_add_i32 m0, s45, 0x10400
	v_add_lshl_u32 v142, v1, v0, 1
	s_add_u32 s8, s38, 0x160000
	global_load_lds_dwordx4 v142, s[38:39]
	s_addc_u32 s9, s39, 0
	s_add_i32 m0, s45, 0x14000
	s_mul_i32 s5, s49, 0x2c0000
	global_load_lds_dwordx4 v138, s[8:9]
	s_add_i32 m0, s45, 0x14400
	s_mul_hi_i32 s3, s49, 0x2c0000
	s_add_u32 s24, s36, s5
	s_addc_u32 s25, s37, s3
	s_add_i32 s46, s45, 0x400
	global_load_lds_dwordx4 v142, s[8:9]
	s_mov_b32 m0, s45
	s_add_u32 s8, s24, 0x160000
	global_load_lds_dwordx4 v136, s[24:25]
	s_mov_b32 m0, s46
	s_addc_u32 s9, s25, 0
	s_add_i32 s47, s45, 0x4000
	global_load_lds_dwordx4 v140, s[24:25]
	s_mov_b32 m0, s47
	s_add_i32 s50, s45, 0x4400
	global_load_lds_dwordx4 v136, s[8:9]
	s_mov_b32 m0, s50
	v_mov_b32_e32 v139, 0
	global_load_lds_dwordx4 v140, s[8:9]
	v_mov_b32_e32 v143, v139
	v_mov_b32_e32 v137, v139
	v_mov_b32_e32 v141, v139
	s_cmp_eq_u32 s1, 1
	s_mov_b32 s51, 0
	s_mov_b32 s56, 0x10000
	v_lshl_add_u64 v[6:7], s[38:39], 0, v[138:139]
	v_lshl_add_u64 v[2:3], s[38:39], 0, v[142:143]
	s_mov_b32 s5, 0x16000
	v_lshl_add_u64 v[0:1], s[24:25], 0, v[136:137]
	s_cselect_b64 s[8:9], -1, 0
	s_cmp_lg_u32 s1, 1
	v_lshl_add_u64 v[4:5], s[24:25], 0, v[140:141]
	s_cbranch_scc1 .LBB0_1130
	s_barrier
.LBB0_1130:
	s_lshl_b32 s2, s2, 5
	s_mov_b64 s[10:11], 0x80
	s_and_b32 s22, s2, 0x60
	s_add_i32 m0, s45, 0x18000
	v_lshl_add_u64 v[6:7], v[6:7], 0, s[10:11]
	s_lshl_b32 s12, s1, 13
	s_lshl_b32 s13, s22, 7
	s_waitcnt vmcnt(2)
	s_barrier
	global_load_lds_dwordx4 v[6:7], off
	v_lshl_add_u64 v[2:3], v[2:3], 0, s[10:11]
	s_add_i32 m0, s45, 0x18400
	s_add_i32 s57, s45, 0x8000
	s_add_i32 s58, s45, 0x8400
	global_load_lds_dwordx4 v[2:3], off
	v_lshl_add_u64 v[0:1], v[0:1], 0, s[10:11]
	s_mov_b32 m0, s57
	s_add_u32 s2, s38, 0x160080
	global_load_lds_dwordx4 v[0:1], off
	v_lshl_add_u64 v[0:1], v[4:5], 0, s[10:11]
	s_mov_b32 m0, s58
	s_addc_u32 s3, s39, 0
	global_load_lds_dwordx4 v[0:1], off
	s_add_i32 m0, s45, 0x1c000
	v_lshl_add_u64 v[0:1], s[2:3], 0, v[138:139]
	global_load_lds_dwordx4 v[0:1], off
	v_lshl_add_u64 v[0:1], s[2:3], 0, v[142:143]
	s_add_i32 m0, s45, 0x1c400
	s_cmpk_lt_u32 s0, 0x100
	global_load_lds_dwordx4 v[0:1], off
	v_bfe_u32 v1, v8, 4, 2
	v_and_b32_e32 v0, 15, v8
	v_lshlrev_b32_e32 v2, 4, v1
	v_lshl_or_b32 v158, s1, 6, v0
	v_lshl_or_b32 v0, v0, 6, v2
	v_lshlrev_b32_e32 v2, 2, v8
	v_and_b32_e32 v2, 32, v2
	v_bitop3_b32 v3, v0, s12, v2 bitop3:0xde
	v_bitop3_b32 v159, v0, s13, v2 bitop3:0xde
	v_cmp_eq_u32_e64 s[2:3], 0, v1
	v_lshl_or_b32 v160, v1, 3, s22
	v_lshrrev_b32_e32 v1, 1, v9
	v_mul_lo_u32 v0, v10, s4
	v_mad_u64_u32 v[0:1], s[0:1], v1, s5, v[0:1]
	v_or_b32_e32 v0, v0, v11
	s_mov_b64 s[14:15], 0x160080
	v_add_lshl_u32 v0, v0, v12, 1
	v_mov_b32_e32 v1, v139
	v_lshl_add_u64 v[144:145], v[0:1], 0, s[14:15]
	v_lshrrev_b32_e32 v1, 1, v13
	v_mul_lo_u32 v0, v14, s4
	v_mad_u64_u32 v[0:1], s[0:1], v1, s5, v[0:1]
	s_waitcnt vmcnt(6)
	v_or_b32_e32 v0, v0, v15
	s_cselect_b64 s[12:13], -1, 0
	v_add_lshl_u32 v0, v0, v16, 1
	v_mov_b32_e32 v1, v139
	s_add_i32 s60, 0, 0x10000
	s_add_i32 s61, 0, 0x14000
	v_lshl_add_u64 v[146:147], v[0:1], 0, s[14:15]
	v_mov_b64_e32 v[148:149], 0x600
	v_mov_b64_e32 v[150:151], 0x5ff
	s_movk_i32 s59, 0xc1
	v_add_u32_e32 v161, s60, v159
	v_add_u32_e32 v162, s61, v159
	v_add_u32_e32 v163, 0, v3
	v_mbcnt_hi_u32_b32 v164, -1, v207
	s_barrier
	s_branch .LBB0_1133

; #define PG8_STAGE(bufoff, gbase, voff) do { _Pragma("unroll") for (int _i = 0; _i < 2; ++_i) \
;         __builtin_amdgcn_global_load_lds((const unsigned*)((const char*)(gbase) + (voff)[_i]), (LAS unsigned*)(lds + (bufoff) + ldsw + _i * 8192), 16, 0, 0); } while (0)
; #define PG8_LDA(dst, b, h) do { _Pragma("unroll") for (int m = 0; m < 4; ++m) _Pragma("unroll") for (int k = 0; k < 2; ++k) dst[m][k] = *(const LAS bf16x8*)(lds + PG8_SA(b, h) + aoff + m * 2048 + k * 1024); } while (0)
; #define PG8_LDB(dst, b, h) do { _Pragma("unroll") for (int n = 0; n < 2; ++n) _Pragma("unroll") for (int k = 0; k < 2; ++k) dst[n][k] = *(const LAS bf16x8*)(lds + PG8_SB(b, h) + boff + n * 2048 + k * 1024); } while (0)
; #define PG8_MMA(ai, bj, At, Bt) do { __builtin_amdgcn_s_setprio(1); _Pragma("unroll") for (int m = 0; m < 4; ++m) _Pragma("unroll") for (int n = 0; n < 2; ++n) _Pragma("unroll") for (int k = 0; k < 2; ++k) \
;         acc[ai][bj][m][n] = __builtin_amdgcn_mfma_f32_16x16x32_bf16(Bt[n][k], At[m][k], acc[ai][bj][m][n], 0, 0, 0); __builtin_amdgcn_s_setprio(0); } while (0)
; #define PG8_WAIT_V(n) asm volatile("s_waitcnt vmcnt(" #n ")" ::: "memory")
; #define PG8_WAIT_L(n) asm volatile("s_waitcnt lgkmcnt(" #n ")" ::: "memory")
; #define PG8_BAR __builtin_amdgcn_s_barrier()
; #define PG8_SCHED __builtin_amdgcn_sched_barrier(0)
; template <class Epi, class Sched, bool ALIGN_EPI, bool SP2>
; __device__ __forceinline__ void gemm_phase(LAS unsigned char* lds, const Gemm g, const Sched& S, const Epi& E) {
;     ...
;             PG8_LDB(B0, 0, 0); PG8_LDB(B1, 0, 1); PG8_SCHED; PG8_LDA(At, 0, 0); PG8_STAGE(PG8_SA(1, 1), a1 + hstep, voffA);
;             PG8_WAIT_V(8); PG8_WAIT_L(0); PG8_BAR; PG8_MMA(0, 0, At, B0); PG8_MMA(0, 1, At, B1); PG8_BAR; PG8_SCHED;
;             PG8_LDA(At, 0, 1); PG8_STAGE(PG8_SB(0, 0), b2, voffB); PG8_STAGE(PG8_SB(0, 1), b2 + hstepB, voffB); PG8_STAGE(PG8_SA(0, 0), a2, voffA);
;             PG8_WAIT_V(8); PG8_WAIT_L(0); PG8_BAR; PG8_MMA(1, 0, At, B0); PG8_MMA(1, 1, At, B1); PG8_BAR; PG8_SCHED;
.LBB0_1140:
	ds_read_b128 v[128:131], v161
	ds_read_b128 v[132:135], v161 offset:1024
	ds_read_b128 v[152:155], v161 offset:2048
	ds_read_b128 v[166:169], v161 offset:3072
	ds_read_b128 v[170:173], v162
	ds_read_b128 v[174:177], v162 offset:1024
	ds_read_b128 v[178:181], v162 offset:2048
	ds_read_b128 v[182:185], v162 offset:3072
	s_add_u32 s38, s24, 0x100
	s_addc_u32 s39, s25, 0
	s_cmpk_eq_i32 s65, 0x54
	s_cselect_b32 s43, s1, s39
	s_cselect_b32 s42, s0, s38
	s_cselect_b32 s41, s23, s64
	s_cselect_b32 s40, s22, s33
	v_lshl_add_u64 v[156:157], s[24:25], 0, v[144:145]
	s_add_i32 m0, s45, 0xc000
	ds_read_b128 v[186:189], v163
	ds_read_b128 v[190:193], v163 offset:1024
	ds_read_b128 v[194:197], v163 offset:2048
	ds_read_b128 v[198:201], v163 offset:3072
	ds_read_b128 v[202:205], v163 offset:4096
	ds_read_b128 v[208:211], v163 offset:5120
	ds_read_b128 v[212:215], v163 offset:6144
	ds_read_b128 v[216:219], v163 offset:7168
	global_load_lds_dwordx4 v[156:157], off
	v_lshl_add_u64 v[156:157], s[24:25], 0, v[146:147]
	s_add_i32 m0, s45, 0xc400
	s_nop 0
	global_load_lds_dwordx4 v[156:157], off
	s_waitcnt vmcnt(8)
	s_waitcnt lgkmcnt(0)
	s_barrier
	s_setprio 1
	v_mfma_f32_16x16x32_bf16 v[124:127], v[128:131], v[186:189], v[124:127]
	v_mfma_f32_16x16x32_bf16 v[120:123], v[152:155], v[186:189], v[120:123]
	v_mfma_f32_16x16x32_bf16 v[108:111], v[128:131], v[194:197], v[108:111]
	v_mfma_f32_16x16x32_bf16 v[104:107], v[152:155], v[194:197], v[104:107]
	v_mfma_f32_16x16x32_bf16 v[92:95], v[128:131], v[202:205], v[92:95]
	v_mfma_f32_16x16x32_bf16 v[88:91], v[152:155], v[202:205], v[88:91]
	v_mfma_f32_16x16x32_bf16 v[76:79], v[128:131], v[212:215], v[76:79]
	v_mfma_f32_16x16x32_bf16 v[72:75], v[152:155], v[212:215], v[72:75]
	v_mfma_f32_16x16x32_bf16 v[124:127], v[132:135], v[190:193], v[124:127]
	v_mfma_f32_16x16x32_bf16 v[120:123], v[166:169], v[190:193], v[120:123]
	v_mfma_f32_16x16x32_bf16 v[108:111], v[132:135], v[198:201], v[108:111]
	v_mfma_f32_16x16x32_bf16 v[104:107], v[166:169], v[198:201], v[104:107]
	v_mfma_f32_16x16x32_bf16 v[92:95], v[132:135], v[208:211], v[92:95]
	v_mfma_f32_16x16x32_bf16 v[88:91], v[166:169], v[208:211], v[88:91]
	v_mfma_f32_16x16x32_bf16 v[76:79], v[132:135], v[216:219], v[76:79]
	v_mfma_f32_16x16x32_bf16 v[72:75], v[166:169], v[216:219], v[72:75]
	v_mfma_f32_16x16x32_bf16 v[116:119], v[170:173], v[186:189], v[116:119]
	v_mfma_f32_16x16x32_bf16 v[112:115], v[178:181], v[186:189], v[112:115]
	v_mfma_f32_16x16x32_bf16 v[100:103], v[170:173], v[194:197], v[100:103]
	v_mfma_f32_16x16x32_bf16 v[96:99], v[178:181], v[194:197], v[96:99]
	v_mfma_f32_16x16x32_bf16 v[84:87], v[170:173], v[202:205], v[84:87]
	v_mfma_f32_16x16x32_bf16 v[80:83], v[178:181], v[202:205], v[80:83]
	v_mfma_f32_16x16x32_bf16 v[68:71], v[170:173], v[212:215], v[68:71]
	v_mfma_f32_16x16x32_bf16 v[64:67], v[178:181], v[212:215], v[64:67]
	v_mfma_f32_16x16x32_bf16 v[116:119], v[174:177], v[190:193], v[116:119]
	v_mfma_f32_16x16x32_bf16 v[112:115], v[182:185], v[190:193], v[112:115]
	v_mfma_f32_16x16x32_bf16 v[100:103], v[174:177], v[198:201], v[100:103]
	v_mfma_f32_16x16x32_bf16 v[96:99], v[182:185], v[198:201], v[96:99]
	v_mfma_f32_16x16x32_bf16 v[84:87], v[174:177], v[208:211], v[84:87]
	v_mfma_f32_16x16x32_bf16 v[80:83], v[182:185], v[208:211], v[80:83]
	v_mfma_f32_16x16x32_bf16 v[68:71], v[174:177], v[216:219], v[68:71]
	v_mfma_f32_16x16x32_bf16 v[64:67], v[182:185], v[216:219], v[64:67]
	s_setprio 0
	s_barrier
	s_add_i32 s14, s60, s44
	v_lshl_add_u64 v[156:157], s[40:41], 0, v[138:139]
	s_mov_b32 m0, s14
	ds_read_b128 v[186:189], v163 offset:16384
	ds_read_b128 v[190:193], v163 offset:17408
	ds_read_b128 v[194:197], v163 offset:18432
	ds_read_b128 v[198:201], v163 offset:19456
	ds_read_b128 v[202:205], v163 offset:20480
	ds_read_b128 v[208:211], v163 offset:21504
	ds_read_b128 v[212:215], v163 offset:22528
	ds_read_b128 v[216:219], v163 offset:23552
	global_load_lds_dwordx4 v[156:157], off
	s_add_i32 m0, s14, 0x400
	s_add_u32 s14, s40, 0x160000
	v_lshl_add_u64 v[220:221], s[40:41], 0, v[142:143]
	s_addc_u32 s15, s41, 0
	s_add_i32 s24, s61, s44
	global_load_lds_dwordx4 v[220:221], off
	v_lshl_add_u64 v[222:223], s[14:15], 0, v[138:139]
	s_mov_b32 m0, s24
	v_lshl_add_u64 v[224:225], s[42:43], 0, v[140:141]
	global_load_lds_dwordx4 v[222:223], off
	v_lshl_add_u64 v[222:223], s[14:15], 0, v[142:143]
	s_add_i32 m0, s24, 0x400
	s_nop 0
	global_load_lds_dwordx4 v[222:223], off
	v_lshl_add_u64 v[222:223], s[42:43], 0, v[136:137]
	s_mov_b32 m0, s45
	s_nop 0
	global_load_lds_dwordx4 v[222:223], off
	s_mov_b32 m0, s46
	s_nop 0
	global_load_lds_dwordx4 v[224:225], off
	s_waitcnt vmcnt(8)
	s_waitcnt lgkmcnt(0)
	s_barrier
; #define PG8_STAGE(bufoff, gbase, voff) do { _Pragma("unroll") for (int _i = 0; _i < 2; ++_i) \
;         __builtin_amdgcn_global_load_lds((const unsigned*)((const char*)(gbase) + (voff)[_i]), (LAS unsigned*)(lds + (bufoff) + ldsw + _i * 8192), 16, 0, 0); } while (0)
; #define PG8_LDA(dst, b, h) do { _Pragma("unroll") for (int m = 0; m < 4; ++m) _Pragma("unroll") for (int k = 0; k < 2; ++k) dst[m][k] = *(const LAS bf16x8*)(lds + PG8_SA(b, h) + aoff + m * 2048 + k * 1024); } while (0)
; #define PG8_LDB(dst, b, h) do { _Pragma("unroll") for (int n = 0; n < 2; ++n) _Pragma("unroll") for (int k = 0; k < 2; ++k) dst[n][k] = *(const LAS bf16x8*)(lds + PG8_SB(b, h) + boff + n * 2048 + k * 1024); } while (0)
; #define PG8_MMA(ai, bj, At, Bt) do { __builtin_amdgcn_s_setprio(1); _Pragma("unroll") for (int m = 0; m < 4; ++m) _Pragma("unroll") for (int n = 0; n < 2; ++n) _Pragma("unroll") for (int k = 0; k < 2; ++k) \
;         acc[ai][bj][m][n] = __builtin_amdgcn_mfma_f32_16x16x32_bf16(Bt[n][k], At[m][k], acc[ai][bj][m][n], 0, 0, 0); __builtin_amdgcn_s_setprio(0); } while (0)
; #define PG8_WAIT_V(n) asm volatile("s_waitcnt vmcnt(" #n ")" ::: "memory")
; #define PG8_WAIT_L(n) asm volatile("s_waitcnt lgkmcnt(" #n ")" ::: "memory")
; #define PG8_BAR __builtin_amdgcn_s_barrier()
; #define PG8_SCHED __builtin_amdgcn_sched_barrier(0)
; template <class Epi, class Sched, bool ALIGN_EPI, bool SP2>
; __device__ __forceinline__ void gemm_phase(LAS unsigned char* lds, const Gemm g, const Sched& S, const Epi& E) {
;     ...
;             PG8_WAIT_V(8); PG8_WAIT_L(0); PG8_BAR; PG8_MMA(1, 0, At, B0); PG8_MMA(1, 1, At, B1); PG8_BAR; PG8_SCHED;
;             PG8_LDB(B0, 1, 0); PG8_LDB(B1, 1, 1); PG8_SCHED; PG8_LDA(At, 1, 0); PG8_STAGE(PG8_SA(0, 1), a2 + hstep, voffA);
;             PG8_WAIT_V(8); PG8_WAIT_L(0); PG8_BAR; PG8_MMA(0, 0, At, B0); PG8_MMA(0, 1, At, B1); PG8_BAR; PG8_SCHED;
;             PG8_LDA(At, 1, 1); PG8_STAGE(PG8_SB(1, 0), b3, voffB); PG8_STAGE(PG8_SB(1, 1), b3 + hstepB, voffB); PG8_STAGE(PG8_SA(1, 0), a3, voffA);
	s_setprio 1
	v_mfma_f32_16x16x32_bf16 v[60:63], v[128:131], v[186:189], v[60:63]
	v_mfma_f32_16x16x32_bf16 v[56:59], v[152:155], v[186:189], v[56:59]
	v_mfma_f32_16x16x32_bf16 v[44:47], v[128:131], v[194:197], v[44:47]
	v_mfma_f32_16x16x32_bf16 v[40:43], v[152:155], v[194:197], v[40:43]
	v_mfma_f32_16x16x32_bf16 v[28:31], v[128:131], v[202:205], v[28:31]
	v_mfma_f32_16x16x32_bf16 v[24:27], v[152:155], v[202:205], v[24:27]
	v_mfma_f32_16x16x32_bf16 v[12:15], v[128:131], v[212:215], v[12:15]
	v_mfma_f32_16x16x32_bf16 v[8:11], v[152:155], v[212:215], v[8:11]
	v_mfma_f32_16x16x32_bf16 v[60:63], v[132:135], v[190:193], v[60:63]
	v_mfma_f32_16x16x32_bf16 v[56:59], v[166:169], v[190:193], v[56:59]
	v_mfma_f32_16x16x32_bf16 v[44:47], v[132:135], v[198:201], v[44:47]
	v_mfma_f32_16x16x32_bf16 v[40:43], v[166:169], v[198:201], v[40:43]
	v_mfma_f32_16x16x32_bf16 v[28:31], v[132:135], v[208:211], v[28:31]
	v_mfma_f32_16x16x32_bf16 v[24:27], v[166:169], v[208:211], v[24:27]
	v_mfma_f32_16x16x32_bf16 v[12:15], v[132:135], v[216:219], v[12:15]
	v_mfma_f32_16x16x32_bf16 v[8:11], v[166:169], v[216:219], v[8:11]
	v_mfma_f32_16x16x32_bf16 v[52:55], v[170:173], v[186:189], v[52:55]
	v_mfma_f32_16x16x32_bf16 v[48:51], v[178:181], v[186:189], v[48:51]
	v_mfma_f32_16x16x32_bf16 v[36:39], v[170:173], v[194:197], v[36:39]
	v_mfma_f32_16x16x32_bf16 v[32:35], v[178:181], v[194:197], v[32:35]
	v_mfma_f32_16x16x32_bf16 v[20:23], v[170:173], v[202:205], v[20:23]
	v_mfma_f32_16x16x32_bf16 v[16:19], v[178:181], v[202:205], v[16:19]
	v_mfma_f32_16x16x32_bf16 v[4:7], v[170:173], v[212:215], v[4:7]
	v_mfma_f32_16x16x32_bf16 v[0:3], v[178:181], v[212:215], v[0:3]
	v_mfma_f32_16x16x32_bf16 v[52:55], v[174:177], v[190:193], v[52:55]
	v_mfma_f32_16x16x32_bf16 v[48:51], v[182:185], v[190:193], v[48:51]
	v_mfma_f32_16x16x32_bf16 v[36:39], v[174:177], v[198:201], v[36:39]
	v_mfma_f32_16x16x32_bf16 v[32:35], v[182:185], v[198:201], v[32:35]
	v_mfma_f32_16x16x32_bf16 v[20:23], v[174:177], v[208:211], v[20:23]
	v_mfma_f32_16x16x32_bf16 v[16:19], v[182:185], v[208:211], v[16:19]
	v_mfma_f32_16x16x32_bf16 v[4:7], v[174:177], v[216:219], v[4:7]
	v_mfma_f32_16x16x32_bf16 v[0:3], v[182:185], v[216:219], v[0:3]
	s_setprio 0
	s_barrier
	s_add_i32 s24, 0, 0x18000
	v_add_u32_e32 v165, s24, v159
	s_add_i32 s25, 0, 0x1c000
	ds_read_b128 v[128:131], v165
	ds_read_b128 v[132:135], v165 offset:1024
	ds_read_b128 v[152:155], v165 offset:2048
	ds_read_b128 v[166:169], v165 offset:3072
	v_add_u32_e32 v165, s25, v159
	ds_read_b128 v[170:173], v165
	ds_read_b128 v[174:177], v165 offset:1024
	ds_read_b128 v[178:181], v165 offset:2048
	ds_read_b128 v[182:185], v165 offset:3072
	s_add_u32 s14, s42, 0x160000
	s_addc_u32 s15, s43, 0
	s_mov_b32 m0, s47
	v_lshl_add_u64 v[226:227], s[14:15], 0, v[136:137]
	ds_read_b128 v[186:189], v163 offset:32768
	ds_read_b128 v[190:193], v163 offset:33792
	ds_read_b128 v[194:197], v163 offset:34816
	ds_read_b128 v[198:201], v163 offset:35840
	ds_read_b128 v[202:205], v163 offset:36864
	ds_read_b128 v[208:211], v163 offset:37888
	ds_read_b128 v[212:215], v163 offset:38912
	ds_read_b128 v[216:219], v163 offset:39936
	global_load_lds_dwordx4 v[226:227], off
	v_lshl_add_u64 v[226:227], s[14:15], 0, v[140:141]
	s_mov_b32 m0, s50
	s_nop 0
	global_load_lds_dwordx4 v[226:227], off
	s_waitcnt vmcnt(8)
	s_waitcnt lgkmcnt(0)
	s_barrier
	s_setprio 1
	v_mfma_f32_16x16x32_bf16 v[124:127], v[128:131], v[186:189], v[124:127]
	v_mfma_f32_16x16x32_bf16 v[120:123], v[152:155], v[186:189], v[120:123]
	v_mfma_f32_16x16x32_bf16 v[108:111], v[128:131], v[194:197], v[108:111]
	v_mfma_f32_16x16x32_bf16 v[104:107], v[152:155], v[194:197], v[104:107]
	v_mfma_f32_16x16x32_bf16 v[92:95], v[128:131], v[202:205], v[92:95]
	v_mfma_f32_16x16x32_bf16 v[88:91], v[152:155], v[202:205], v[88:91]
	v_mfma_f32_16x16x32_bf16 v[76:79], v[128:131], v[212:215], v[76:79]
	v_mfma_f32_16x16x32_bf16 v[72:75], v[152:155], v[212:215], v[72:75]
	v_mfma_f32_16x16x32_bf16 v[124:127], v[132:135], v[190:193], v[124:127]
	v_mfma_f32_16x16x32_bf16 v[120:123], v[166:169], v[190:193], v[120:123]
	v_mfma_f32_16x16x32_bf16 v[108:111], v[132:135], v[198:201], v[108:111]
	v_mfma_f32_16x16x32_bf16 v[104:107], v[166:169], v[198:201], v[104:107]
	v_mfma_f32_16x16x32_bf16 v[92:95], v[132:135], v[208:211], v[92:95]
	v_mfma_f32_16x16x32_bf16 v[88:91], v[166:169], v[208:211], v[88:91]
	v_mfma_f32_16x16x32_bf16 v[76:79], v[132:135], v[216:219], v[76:79]
	v_mfma_f32_16x16x32_bf16 v[72:75], v[166:169], v[216:219], v[72:75]
	v_mfma_f32_16x16x32_bf16 v[116:119], v[170:173], v[186:189], v[116:119]
	v_mfma_f32_16x16x32_bf16 v[112:115], v[178:181], v[186:189], v[112:115]
	v_mfma_f32_16x16x32_bf16 v[100:103], v[170:173], v[194:197], v[100:103]
	v_mfma_f32_16x16x32_bf16 v[96:99], v[178:181], v[194:197], v[96:99]
	v_mfma_f32_16x16x32_bf16 v[84:87], v[170:173], v[202:205], v[84:87]
	v_mfma_f32_16x16x32_bf16 v[80:83], v[178:181], v[202:205], v[80:83]
	v_mfma_f32_16x16x32_bf16 v[68:71], v[170:173], v[212:215], v[68:71]
	v_mfma_f32_16x16x32_bf16 v[64:67], v[178:181], v[212:215], v[64:67]
	v_mfma_f32_16x16x32_bf16 v[116:119], v[174:177], v[190:193], v[116:119]
	v_mfma_f32_16x16x32_bf16 v[112:115], v[182:185], v[190:193], v[112:115]
	v_mfma_f32_16x16x32_bf16 v[100:103], v[174:177], v[198:201], v[100:103]
	v_mfma_f32_16x16x32_bf16 v[96:99], v[182:185], v[198:201], v[96:99]
	v_mfma_f32_16x16x32_bf16 v[84:87], v[174:177], v[208:211], v[84:87]
	v_mfma_f32_16x16x32_bf16 v[80:83], v[182:185], v[208:211], v[80:83]
	v_mfma_f32_16x16x32_bf16 v[68:71], v[174:177], v[216:219], v[68:71]
	v_mfma_f32_16x16x32_bf16 v[64:67], v[182:185], v[216:219], v[64:67]
	s_setprio 0
	s_barrier
; #define PG8_STAGE(bufoff, gbase, voff) do { _Pragma("unroll") for (int _i = 0; _i < 2; ++_i) \
;         __builtin_amdgcn_global_load_lds((const unsigned*)((const char*)(gbase) + (voff)[_i]), (LAS unsigned*)(lds + (bufoff) + ldsw + _i * 8192), 16, 0, 0); } while (0)
; #define PG8_LDA(dst, b, h) do { _Pragma("unroll") for (int m = 0; m < 4; ++m) _Pragma("unroll") for (int k = 0; k < 2; ++k) dst[m][k] = *(const LAS bf16x8*)(lds + PG8_SA(b, h) + aoff + m * 2048 + k * 1024); } while (0)
; #define PG8_MMA(ai, bj, At, Bt) do { __builtin_amdgcn_s_setprio(1); _Pragma("unroll") for (int m = 0; m < 4; ++m) _Pragma("unroll") for (int n = 0; n < 2; ++n) _Pragma("unroll") for (int k = 0; k < 2; ++k) \
;         acc[ai][bj][m][n] = __builtin_amdgcn_mfma_f32_16x16x32_bf16(Bt[n][k], At[m][k], acc[ai][bj][m][n], 0, 0, 0); __builtin_amdgcn_s_setprio(0); } while (0)
; #define PG8_WAIT_V(n) asm volatile("s_waitcnt vmcnt(" #n ")" ::: "memory")
; #define PG8_WAIT_L(n) asm volatile("s_waitcnt lgkmcnt(" #n ")" ::: "memory")
; #define PG8_BAR __builtin_amdgcn_s_barrier()
; #define PG8_SCHED __builtin_amdgcn_sched_barrier(0)
; template <class Epi, class Sched, bool ALIGN_EPI, bool SP2>
; __device__ __forceinline__ void gemm_phase(LAS unsigned char* lds, const Gemm g, const Sched& S, const Epi& E) {
;     ...
;             PG8_LDA(At, 1, 1); PG8_STAGE(PG8_SB(1, 0), b3, voffB); PG8_STAGE(PG8_SB(1, 1), b3 + hstepB, voffB); PG8_STAGE(PG8_SA(1, 0), a3, voffA);
;             PG8_WAIT_V(8); PG8_WAIT_L(0); PG8_BAR; PG8_MMA(1, 0, At, B0); PG8_MMA(1, 1, At, B1); PG8_BAR; PG8_SCHED;
	s_add_i32 s14, s24, s44
	v_lshl_add_u64 v[156:157], v[156:157], 0, s[10:11]
	s_mov_b32 m0, s14
	ds_read_b128 v[186:189], v163 offset:49152
	ds_read_b128 v[190:193], v163 offset:50176
	ds_read_b128 v[194:197], v163 offset:51200
	ds_read_b128 v[198:201], v163 offset:52224
	ds_read_b128 v[202:205], v163 offset:53248
	ds_read_b128 v[208:211], v163 offset:54272
	ds_read_b128 v[212:215], v163 offset:55296
	ds_read_b128 v[216:219], v163 offset:56320
	global_load_lds_dwordx4 v[156:157], off
	s_add_i32 m0, s14, 0x400
	s_add_u32 s14, s40, 0x160080
	v_lshl_add_u64 v[156:157], v[220:221], 0, s[10:11]
	s_addc_u32 s15, s41, 0
	s_add_i32 s24, s25, s44
	global_load_lds_dwordx4 v[156:157], off
	v_lshl_add_u64 v[156:157], s[14:15], 0, v[138:139]
	s_mov_b32 m0, s24
	s_nop 0
	global_load_lds_dwordx4 v[156:157], off
	v_lshl_add_u64 v[156:157], s[14:15], 0, v[142:143]
	s_add_i32 m0, s24, 0x400
	s_nop 0
	global_load_lds_dwordx4 v[156:157], off
	v_lshl_add_u64 v[156:157], v[222:223], 0, s[10:11]
	s_mov_b32 m0, s57
	s_nop 0
	global_load_lds_dwordx4 v[156:157], off
	v_lshl_add_u64 v[156:157], v[224:225], 0, s[10:11]
	s_mov_b32 m0, s58
	s_nop 0
	global_load_lds_dwordx4 v[156:157], off
	s_waitcnt vmcnt(8)
	s_waitcnt lgkmcnt(0)
	s_barrier
	s_setprio 1
	v_mfma_f32_16x16x32_bf16 v[60:63], v[128:131], v[186:189], v[60:63]
	v_mfma_f32_16x16x32_bf16 v[56:59], v[152:155], v[186:189], v[56:59]
	v_mfma_f32_16x16x32_bf16 v[44:47], v[128:131], v[194:197], v[44:47]
	v_mfma_f32_16x16x32_bf16 v[40:43], v[152:155], v[194:197], v[40:43]
	v_mfma_f32_16x16x32_bf16 v[28:31], v[128:131], v[202:205], v[28:31]
	v_mfma_f32_16x16x32_bf16 v[24:27], v[152:155], v[202:205], v[24:27]
	v_mfma_f32_16x16x32_bf16 v[12:15], v[128:131], v[212:215], v[12:15]
	v_mfma_f32_16x16x32_bf16 v[8:11], v[152:155], v[212:215], v[8:11]
	v_mfma_f32_16x16x32_bf16 v[60:63], v[132:135], v[190:193], v[60:63]
	v_mfma_f32_16x16x32_bf16 v[56:59], v[166:169], v[190:193], v[56:59]
	v_mfma_f32_16x16x32_bf16 v[44:47], v[132:135], v[198:201], v[44:47]
	v_mfma_f32_16x16x32_bf16 v[40:43], v[166:169], v[198:201], v[40:43]
	v_mfma_f32_16x16x32_bf16 v[28:31], v[132:135], v[208:211], v[28:31]
	v_mfma_f32_16x16x32_bf16 v[24:27], v[166:169], v[208:211], v[24:27]
	v_mfma_f32_16x16x32_bf16 v[12:15], v[132:135], v[216:219], v[12:15]
	v_mfma_f32_16x16x32_bf16 v[8:11], v[166:169], v[216:219], v[8:11]
	v_mfma_f32_16x16x32_bf16 v[52:55], v[170:173], v[186:189], v[52:55]
	v_mfma_f32_16x16x32_bf16 v[48:51], v[178:181], v[186:189], v[48:51]
	v_mfma_f32_16x16x32_bf16 v[36:39], v[170:173], v[194:197], v[36:39]
	v_mfma_f32_16x16x32_bf16 v[32:35], v[178:181], v[194:197], v[32:35]
	v_mfma_f32_16x16x32_bf16 v[20:23], v[170:173], v[202:205], v[20:23]
	v_mfma_f32_16x16x32_bf16 v[16:19], v[178:181], v[202:205], v[16:19]
	v_mfma_f32_16x16x32_bf16 v[4:7], v[170:173], v[212:215], v[4:7]
	v_mfma_f32_16x16x32_bf16 v[0:3], v[178:181], v[212:215], v[0:3]
	v_mfma_f32_16x16x32_bf16 v[52:55], v[174:177], v[190:193], v[52:55]
	v_mfma_f32_16x16x32_bf16 v[48:51], v[182:185], v[190:193], v[48:51]
	v_mfma_f32_16x16x32_bf16 v[36:39], v[174:177], v[198:201], v[36:39]
	v_mfma_f32_16x16x32_bf16 v[32:35], v[182:185], v[198:201], v[32:35]
	v_mfma_f32_16x16x32_bf16 v[20:23], v[174:177], v[208:211], v[20:23]
	v_mfma_f32_16x16x32_bf16 v[16:19], v[182:185], v[208:211], v[16:19]
	v_mfma_f32_16x16x32_bf16 v[4:7], v[174:177], v[216:219], v[4:7]
	v_mfma_f32_16x16x32_bf16 v[0:3], v[182:185], v[216:219], v[0:3]
	s_setprio 0
	s_barrier
	s_add_i32 s65, s65, 2
	s_add_u32 s33, s33, 0x100
	s_addc_u32 s64, s64, 0
	s_cmpk_gt_u32 s65, 0x55
	s_mov_b64 s[24:25], s[38:39]
	s_cbranch_scc0 .LBB0_1140
	s_and_b64 vcc, exec, s[12:13]
	s_cbranch_vccz .LBB0_1143
	s_barrier
